# G1 gated branch epilogue: gate loads hoisted (14 up front into idle fragment registers + 2 after the second store) instead of 16 load-wait round trips per tile
# speedup vs baseline: 1.0267x; 1.0037x over previous
;     __device__ __forceinline__ void operator()(const f32x4 (&acc)[2][2][4][2], const pg8::Unit& u, int wr, int wc, int fr, int fq) const {
;         const int gi = u.pn >> 3, pn = u.pn & 7;
;         if (gi == 0) { pg8::Unit u2; u2.pm = u.pm; u2.pn = pn; EpiPair<1> e{ys5, 1024, glu_bias}; e(acc, u2, wr, wc, fr, fq); return; }
;         bf16_t* br = (gi == 1) ? br0 : br1;
;         const int row0 = (u.pm % MT) * 256 + wr * 64 + fr, col0 = pn * 256 + wc * 32 + 8 * fq;
; #pragma unroll
;         for (int ai = 0; ai < 2; ++ai)
; #pragma unroll
;             for (int m = 0; m < 4; ++m) { const int row = row0 + ai * 128 + m * 16;
; #pragma unroll
;                 for (int bj = 0; bj < 2; ++bj) { const int col = col0 + bj * 128;
;                     const u32x4 gw = *(const u32x4*)(P + (size_t)row * NINP + GATEOFF + (gi - 1) * 2048 + col); float gt[8]; unpack8(gw, gt);
.LBB0_687:
	v_readlane_b32 s48, v255, 14
	s_mov_b64 s[26:27], -1
	s_cmp_gt_u32 s22, 7
	s_mul_hi_i32 s15, s24, 0x78787879
	v_readlane_b32 s49, v255, 15
	v_readlane_b32 s50, v255, 16
	v_readlane_b32 s51, v255, 17
	v_readlane_b32 s52, v255, 18
	v_readlane_b32 s53, v255, 19
	v_readlane_b32 s54, v255, 20
	v_readlane_b32 s55, v255, 21
	v_readlane_b32 s56, v255, 22
	v_readlane_b32 s57, v255, 23
	v_readlane_b32 s58, v255, 24
	v_readlane_b32 s59, v255, 25
	v_readlane_b32 s60, v255, 26
	v_readlane_b32 s61, v255, 27
	v_readlane_b32 s62, v255, 28
	v_readlane_b32 s63, v255, 29
	s_cbranch_scc0 .LBB0_689
	s_ashr_i32 s17, s22, 3
	v_readlane_b32 s26, v252, 60
	s_cmp_eq_u32 s17, 1
	v_readlane_b32 s27, v252, 61
	s_cselect_b32 s27, s27, s91
	s_cselect_b32 s26, s26, s90
	s_lshr_b32 s28, s15, 31
	s_lshr_b32 s29, s15, 4
	s_add_i32 s28, s29, s28
	s_mul_i32 s28, s28, 34
	s_sub_i32 s28, s24, s28
	v_lshl_add_u32 v130, s28, 8, v149
	s_lshl_b32 s28, s22, 8
	s_and_b32 s28, s28, 0x700
	s_lshl_b32 s17, s17, 11
	v_ashrrev_i32_e32 v131, 31, v130
	v_or_b32_e32 v0, s28, v166
	s_add_i32 s28, s17, 0xfffff800
	v_lshlrev_b64 v[132:133], 12, v[130:131]
	s_ashr_i32 s29, s28, 31
	v_lshl_add_u64 v[134:135], s[26:27], 0, v[132:133]
	v_mov_b64_e32 v[132:133], s[96:97]
	v_mad_i64_i32 v[136:137], s[30:31], v130, s79, v[132:133]
	s_lshl_b64 s[28:29], s[28:29], 1
	v_lshl_add_u64 v[136:137], v[136:137], 0, s[28:29]
	v_lshlrev_b32_e32 v0, 1, v0
	v_lshl_add_u64 v[138:139], v[136:137], 0, v[0:1]
	s_mov_b64 s[60:61], 0x3440
	s_movk_i32 s17, 0x3000
	v_lshl_add_u64 v[136:137], v[138:139], 0, s[60:61]
	v_add_co_u32_e32 v138, vcc, s17, v138
	v_lshl_add_u64 v[134:135], v[134:135], 0, v[0:1]
	s_nop 0
	v_addc_co_u32_e32 v139, vcc, 0, v139, vcc
	v_mad_i64_i32 v[250:251], s[30:31], v130, s79, v[132:133]
	v_lshl_add_u64 v[250:251], v[250:251], 0, s[28:29]
	v_lshl_add_u64 v[250:251], v[250:251], 0, v[0:1]
	v_add_co_u32_e32 v250, vcc, s17, v250
	s_nop 1
	v_addc_co_u32_e32 v251, vcc, 0, v251, vcc
	global_load_dwordx4 v[168:171], v[250:251], off offset:1088
	global_load_dwordx4 v[172:175], v[250:251], off offset:1344
	v_or_b32_e32 v213, 16, v130
	v_mad_i64_i32 v[250:251], s[30:31], v213, s79, v[132:133]
	v_lshl_add_u64 v[250:251], v[250:251], 0, s[28:29]
	v_lshl_add_u64 v[250:251], v[250:251], 0, v[0:1]
	v_add_co_u32_e32 v250, vcc, s17, v250
	s_nop 1
	v_addc_co_u32_e32 v251, vcc, 0, v251, vcc
	global_load_dwordx4 v[176:179], v[250:251], off offset:1088
	global_load_dwordx4 v[180:183], v[250:251], off offset:1344
	v_or_b32_e32 v213, 32, v130
	v_mad_i64_i32 v[250:251], s[30:31], v213, s79, v[132:133]
	v_lshl_add_u64 v[250:251], v[250:251], 0, s[28:29]
	v_lshl_add_u64 v[250:251], v[250:251], 0, v[0:1]
	v_add_co_u32_e32 v250, vcc, s17, v250
	s_nop 1
	v_addc_co_u32_e32 v251, vcc, 0, v251, vcc
	global_load_dwordx4 v[184:187], v[250:251], off offset:1088
	global_load_dwordx4 v[214:217], v[250:251], off offset:1344
	v_or_b32_e32 v213, 48, v130
	v_mad_i64_i32 v[250:251], s[30:31], v213, s79, v[132:133]
	v_lshl_add_u64 v[250:251], v[250:251], 0, s[28:29]
	v_lshl_add_u64 v[250:251], v[250:251], 0, v[0:1]
	v_add_co_u32_e32 v250, vcc, s17, v250
	s_nop 1
	v_addc_co_u32_e32 v251, vcc, 0, v251, vcc
	global_load_dwordx4 v[218:221], v[250:251], off offset:1088
	global_load_dwordx4 v[222:225], v[250:251], off offset:1344
	v_add_u32_e32 v213, 0x80, v130
	v_mad_i64_i32 v[250:251], s[30:31], v213, s79, v[132:133]
	v_lshl_add_u64 v[250:251], v[250:251], 0, s[28:29]
	v_lshl_add_u64 v[250:251], v[250:251], 0, v[0:1]
	v_add_co_u32_e32 v250, vcc, s17, v250
	s_nop 1
	v_addc_co_u32_e32 v251, vcc, 0, v251, vcc
	global_load_dwordx4 v[226:229], v[250:251], off offset:1088
	global_load_dwordx4 v[230:233], v[250:251], off offset:1344
	v_add_u32_e32 v213, 0x90, v130
	v_mad_i64_i32 v[250:251], s[30:31], v213, s79, v[132:133]
	v_lshl_add_u64 v[250:251], v[250:251], 0, s[28:29]
	v_lshl_add_u64 v[250:251], v[250:251], 0, v[0:1]
	v_add_co_u32_e32 v250, vcc, s17, v250
	s_nop 1
	v_addc_co_u32_e32 v251, vcc, 0, v251, vcc
	global_load_dwordx4 v[234:237], v[250:251], off offset:1088
	global_load_dwordx4 v[238:241], v[250:251], off offset:1344
	v_add_u32_e32 v213, 0xa0, v130
	v_mad_i64_i32 v[250:251], s[30:31], v213, s79, v[132:133]
	v_lshl_add_u64 v[250:251], v[250:251], 0, s[28:29]
	v_lshl_add_u64 v[250:251], v[250:251], 0, v[0:1]
	v_add_co_u32_e32 v250, vcc, s17, v250
	s_nop 1
	v_addc_co_u32_e32 v251, vcc, 0, v251, vcc
	global_load_dwordx4 v[242:245], v[250:251], off offset:1088
	global_load_dwordx4 v[246:249], v[250:251], off offset:1344
	v_add_u32_e32 v213, 0xb0, v130
	v_mad_i64_i32 v[250:251], s[30:31], v213, s79, v[132:133]
	v_lshl_add_u64 v[250:251], v[250:251], 0, s[28:29]
	v_lshl_add_u64 v[250:251], v[250:251], 0, v[0:1]
	v_add_co_u32_e32 v250, vcc, s17, v250
	s_nop 1
	v_addc_co_u32_e32 v251, vcc, 0, v251, vcc
	s_waitcnt vmcnt(13)
; __device__ __forceinline__ unsigned pk2(float lo, float hi) { return pg8::cvt_pk_bf16(lo, hi); }
; __device__ __forceinline__ float sigmoidf_(float x) { return 1.f / (1.f + __expf(-x)); }
;     __device__ __forceinline__ void operator()(const f32x4 (&acc)[2][2][4][2], const pg8::Unit& u, int wr, int wc, int fr, int fq) const {
;     ...
;                     const u32x4 gw = *(const u32x4*)(P + (size_t)row * NINP + GATEOFF + (gi - 1) * 2048 + col); float gt[8]; unpack8(gw, gt);
;                     const f32x4 v0 = acc[ai][bj][m][0], v1 = acc[ai][bj][m][1];
;                     float o[8];
; #pragma unroll
;                     for (int j = 0; j < 4; ++j) { o[j] = sigmoidf_(gt[j]) * v0[j]; o[4 + j] = sigmoidf_(gt[4 + j]) * v1[j]; }
;                     u32x4 w; w.x = pk2(o[0], o[1]); w.y = pk2(o[2], o[3]); w.z = pk2(o[4], o[5]); w.w = pk2(o[6], o[7]);
;                     *(u32x4*)(br + (size_t)row * D + col) = w; } }
	s_nop 1
	v_mov_b32_e32 v138, v168
	v_mov_b32_e32 v139, v169
	v_mov_b32_e32 v140, v170
	v_mov_b32_e32 v141, v171
	v_lshlrev_b32_e32 v144, 16, v139
	v_and_b32_e32 v145, 0xffff0000, v139
	v_lshlrev_b32_e32 v139, 16, v140
	v_lshlrev_b32_e32 v142, 16, v138
	v_and_b32_e32 v143, 0xffff0000, v138
	v_mul_f32_e32 v139, 0xbfb8aa3b, v139
	v_and_b32_e32 v162, 0xffff0000, v140
	v_mul_f32_e32 v138, 0xbfb8aa3b, v142
	v_exp_f32_e32 v140, v139
	v_mul_f32_e32 v139, 0xbfb8aa3b, v143
	v_exp_f32_e32 v138, v138
	v_exp_f32_e32 v139, v139
	v_lshlrev_b32_e32 v163, 16, v141
	v_and_b32_e32 v131, 0xffff0000, v141
	v_mul_f32_e32 v131, 0xbfb8aa3b, v131
	v_pk_add_f32 v[138:139], v[138:139], 1.0 op_sel_hi:[1,0]
	s_nop 0
	v_div_scale_f32 v141, s[30:31], v139, v139, 1.0
	v_rcp_f32_e32 v142, v141
	s_nop 0
	v_fma_f32 v143, -v141, v142, 1.0
	v_fmac_f32_e32 v142, v143, v142
	v_div_scale_f32 v143, vcc, 1.0, v139, 1.0
	v_mul_f32_e32 v164, v143, v142
	v_fma_f32 v165, -v141, v164, v143
	v_fmac_f32_e32 v164, v165, v142
	v_fma_f32 v141, -v141, v164, v143
	v_div_fmas_f32 v141, v141, v142, v164
	v_div_fixup_f32 v139, v141, v139, 1.0
	v_div_scale_f32 v141, s[30:31], v138, v138, 1.0
	v_rcp_f32_e32 v142, v141
	s_nop 0
	v_fma_f32 v143, -v141, v142, 1.0
	v_fmac_f32_e32 v142, v143, v142
	v_div_scale_f32 v143, vcc, 1.0, v138, 1.0
	v_mul_f32_e32 v164, v143, v142
	v_fma_f32 v165, -v141, v164, v143
	v_fmac_f32_e32 v164, v165, v142
	v_fma_f32 v141, -v141, v164, v143
	v_div_fmas_f32 v141, v141, v142, v164
	v_div_fixup_f32 v138, v141, v138, 1.0
	v_mul_f32_e32 v141, 0xbfb8aa3b, v162
	v_exp_f32_e32 v141, v141
	v_pk_mul_f32 v[138:139], v[122:123], v[138:139]
	v_pk_add_f32 v[140:141], v[140:141], 1.0 op_sel_hi:[1,0]
	s_nop 0
	v_div_scale_f32 v142, s[30:31], v141, v141, 1.0
	v_rcp_f32_e32 v143, v142
	v_cvt_pk_bf16_f32 v138, v138, v139
	v_fma_f32 v162, -v142, v143, 1.0
	v_fmac_f32_e32 v143, v162, v143
	v_div_scale_f32 v162, vcc, 1.0, v141, 1.0
	v_mul_f32_e32 v164, v162, v143
	v_fma_f32 v165, -v142, v164, v162
	v_fmac_f32_e32 v164, v165, v143
	v_fma_f32 v142, -v142, v164, v162
	v_div_fmas_f32 v142, v142, v143, v164
	v_div_fixup_f32 v141, v142, v141, 1.0
	v_div_scale_f32 v142, s[30:31], v140, v140, 1.0
	v_rcp_f32_e32 v143, v142
	s_nop 0
	v_fma_f32 v162, -v142, v143, 1.0
	v_fmac_f32_e32 v143, v162, v143
	v_div_scale_f32 v162, vcc, 1.0, v140, 1.0
	v_mul_f32_e32 v164, v162, v143
	v_fma_f32 v165, -v142, v164, v162
	v_fmac_f32_e32 v164, v165, v143
	v_fma_f32 v142, -v142, v164, v162
	v_div_fmas_f32 v142, v142, v143, v164
	v_div_fixup_f32 v140, v142, v140, 1.0
	v_mul_f32_e32 v142, 0xbfb8aa3b, v144
	v_mul_f32_e32 v143, 0xbfb8aa3b, v145
	v_exp_f32_e32 v144, v142
	v_exp_f32_e32 v145, v143
	v_mul_f32_e32 v142, 0xbfb8aa3b, v163
	v_exp_f32_e32 v142, v142
	v_pk_mul_f32 v[140:141], v[118:119], v[140:141]
	v_pk_add_f32 v[144:145], v[144:145], 1.0 op_sel_hi:[1,0]
	v_cvt_pk_bf16_f32 v140, v140, v141
	v_div_scale_f32 v143, s[30:31], v145, v145, 1.0
	v_rcp_f32_e32 v162, v143
	s_nop 0
	v_fma_f32 v163, -v143, v162, 1.0
	v_fmac_f32_e32 v162, v163, v162
	v_div_scale_f32 v163, vcc, 1.0, v145, 1.0
	v_mul_f32_e32 v164, v163, v162
	v_fma_f32 v165, -v143, v164, v163
	v_fmac_f32_e32 v164, v165, v162
	v_fma_f32 v143, -v143, v164, v163
	v_div_fmas_f32 v143, v143, v162, v164
	v_div_fixup_f32 v145, v143, v145, 1.0
	v_div_scale_f32 v143, s[30:31], v144, v144, 1.0
	v_rcp_f32_e32 v162, v143
	s_nop 0
	v_fma_f32 v163, -v143, v162, 1.0
	v_fmac_f32_e32 v162, v163, v162
	v_div_scale_f32 v163, vcc, 1.0, v144, 1.0
	v_mul_f32_e32 v164, v163, v162
	v_fma_f32 v165, -v143, v164, v163
	v_fmac_f32_e32 v164, v165, v162
	v_fma_f32 v143, -v143, v164, v163
	v_div_fmas_f32 v143, v143, v162, v164
	v_div_fixup_f32 v144, v143, v144, 1.0
	v_exp_f32_e32 v143, v131
	v_pk_mul_f32 v[144:145], v[124:125], v[144:145]
	v_pk_add_f32 v[142:143], v[142:143], 1.0 op_sel_hi:[1,0]
	s_nop 0
	v_div_scale_f32 v131, s[30:31], v143, v143, 1.0
	v_rcp_f32_e32 v162, v131
	v_cvt_pk_bf16_f32 v139, v144, v145
	v_fma_f32 v163, -v131, v162, 1.0
	v_fmac_f32_e32 v162, v163, v162
	v_div_scale_f32 v163, vcc, 1.0, v143, 1.0
	v_mul_f32_e32 v164, v163, v162
	v_fma_f32 v165, -v131, v164, v163
	v_fmac_f32_e32 v164, v165, v162
	v_fma_f32 v131, -v131, v164, v163
	v_div_fmas_f32 v131, v131, v162, v164
	v_div_fixup_f32 v143, v131, v143, 1.0
	v_div_scale_f32 v131, s[30:31], v142, v142, 1.0
	v_rcp_f32_e32 v162, v131
	s_nop 0
	v_fma_f32 v163, -v131, v162, 1.0
	v_fmac_f32_e32 v162, v163, v162
	v_div_scale_f32 v163, vcc, 1.0, v142, 1.0
	v_mul_f32_e32 v164, v163, v162
	v_fma_f32 v165, -v131, v164, v163
	v_fmac_f32_e32 v164, v165, v162
	v_fma_f32 v131, -v131, v164, v163
	v_div_fmas_f32 v131, v131, v162, v164
	v_div_fixup_f32 v142, v131, v142, 1.0
	v_pk_mul_f32 v[142:143], v[120:121], v[142:143]
	s_nop 0
	v_cvt_pk_bf16_f32 v141, v142, v143
	global_store_dwordx4 v[134:135], v[138:141], off
	s_waitcnt vmcnt(13)
; __device__ __forceinline__ unsigned pk2(float lo, float hi) { return pg8::cvt_pk_bf16(lo, hi); }
; __device__ __forceinline__ float sigmoidf_(float x) { return 1.f / (1.f + __expf(-x)); }
;     __device__ __forceinline__ void operator()(const f32x4 (&acc)[2][2][4][2], const pg8::Unit& u, int wr, int wc, int fr, int fq) const {
;     ...
;                     const u32x4 gw = *(const u32x4*)(P + (size_t)row * NINP + GATEOFF + (gi - 1) * 2048 + col); float gt[8]; unpack8(gw, gt);
;                     const f32x4 v0 = acc[ai][bj][m][0], v1 = acc[ai][bj][m][1];
;                     float o[8];
; #pragma unroll
;                     for (int j = 0; j < 4; ++j) { o[j] = sigmoidf_(gt[j]) * v0[j]; o[4 + j] = sigmoidf_(gt[4 + j]) * v1[j]; }
;                     u32x4 w; w.x = pk2(o[0], o[1]); w.y = pk2(o[2], o[3]); w.z = pk2(o[4], o[5]); w.w = pk2(o[6], o[7]);
;                     *(u32x4*)(br + (size_t)row * D + col) = w; } }
	s_nop 1
	v_mov_b32_e32 v136, v172
	v_mov_b32_e32 v137, v173
	v_mov_b32_e32 v138, v174
	v_mov_b32_e32 v139, v175
	v_lshlrev_b32_e32 v131, 16, v136
	v_lshlrev_b32_e32 v141, 16, v137
	v_and_b32_e32 v143, 0xffff0000, v137
	v_lshlrev_b32_e32 v137, 16, v138
	v_mul_f32_e32 v131, 0xbfb8aa3b, v131
	v_and_b32_e32 v140, 0xffff0000, v136
	v_exp_f32_e32 v136, v131
	v_mul_f32_e32 v131, 0xbfb8aa3b, v137
	v_and_b32_e32 v142, 0xffff0000, v138
	v_exp_f32_e32 v138, v131
	v_mul_f32_e32 v131, 0xbfb8aa3b, v140
	v_exp_f32_e32 v137, v131
	v_lshlrev_b32_e32 v144, 16, v139
	v_and_b32_e32 v145, 0xffff0000, v139
	v_pk_add_f32 v[136:137], v[136:137], 1.0 op_sel_hi:[1,0]
	s_nop 0
	v_div_scale_f32 v131, s[30:31], v137, v137, 1.0
	v_rcp_f32_e32 v139, v131
	s_nop 0
	v_fma_f32 v140, -v131, v139, 1.0
	v_fmac_f32_e32 v139, v140, v139
	v_div_scale_f32 v140, vcc, 1.0, v137, 1.0
	v_mul_f32_e32 v162, v140, v139
	v_fma_f32 v163, -v131, v162, v140
	v_fmac_f32_e32 v162, v163, v139
	v_fma_f32 v131, -v131, v162, v140
	v_div_fmas_f32 v131, v131, v139, v162
	v_div_fixup_f32 v137, v131, v137, 1.0
	v_div_scale_f32 v131, s[30:31], v136, v136, 1.0
	v_rcp_f32_e32 v139, v131
	s_nop 0
	v_fma_f32 v140, -v131, v139, 1.0
	v_fmac_f32_e32 v139, v140, v139
	v_div_scale_f32 v140, vcc, 1.0, v136, 1.0
	v_mul_f32_e32 v162, v140, v139
	v_fma_f32 v163, -v131, v162, v140
	v_fmac_f32_e32 v162, v163, v139
	v_fma_f32 v131, -v131, v162, v140
	v_div_fmas_f32 v131, v131, v139, v162
	v_div_fixup_f32 v136, v131, v136, 1.0
	v_mul_f32_e32 v131, 0xbfb8aa3b, v142
	v_exp_f32_e32 v139, v131
	v_pk_mul_f32 v[136:137], v[126:127], v[136:137]
	v_pk_add_f32 v[138:139], v[138:139], 1.0 op_sel_hi:[1,0]
	s_nop 0
	v_div_scale_f32 v131, s[30:31], v139, v139, 1.0
	v_rcp_f32_e32 v140, v131
	v_cvt_pk_bf16_f32 v136, v136, v137
	v_fma_f32 v142, -v131, v140, 1.0
	v_fmac_f32_e32 v140, v142, v140
	v_div_scale_f32 v142, vcc, 1.0, v139, 1.0
	v_mul_f32_e32 v162, v142, v140
	v_fma_f32 v163, -v131, v162, v142
	v_fmac_f32_e32 v162, v163, v140
	v_fma_f32 v131, -v131, v162, v142
	v_div_fmas_f32 v131, v131, v140, v162
	v_div_fixup_f32 v139, v131, v139, 1.0
	v_div_scale_f32 v131, s[30:31], v138, v138, 1.0
	v_rcp_f32_e32 v140, v131
	s_nop 0
	v_fma_f32 v142, -v131, v140, 1.0
	v_fmac_f32_e32 v140, v142, v140
	v_div_scale_f32 v142, vcc, 1.0, v138, 1.0
	v_mul_f32_e32 v162, v142, v140
	v_fma_f32 v163, -v131, v162, v142
	v_fmac_f32_e32 v162, v163, v140
	v_fma_f32 v131, -v131, v162, v142
	v_div_fmas_f32 v131, v131, v140, v162
	v_div_fixup_f32 v138, v131, v138, 1.0
	v_mul_f32_e32 v131, 0xbfb8aa3b, v141
	v_exp_f32_e32 v140, v131
	v_mul_f32_e32 v131, 0xbfb8aa3b, v144
	v_exp_f32_e32 v142, v131
	v_mul_f32_e32 v131, 0xbfb8aa3b, v143
	v_exp_f32_e32 v141, v131
	v_pk_mul_f32 v[138:139], v[114:115], v[138:139]
	v_pk_add_f32 v[140:141], v[140:141], 1.0 op_sel_hi:[1,0]
	s_nop 0
	v_div_scale_f32 v131, s[30:31], v141, v141, 1.0
	v_rcp_f32_e32 v143, v131
	v_cvt_pk_bf16_f32 v138, v138, v139
	v_fma_f32 v144, -v131, v143, 1.0
	v_fmac_f32_e32 v143, v144, v143
	v_div_scale_f32 v144, vcc, 1.0, v141, 1.0
	v_mul_f32_e32 v162, v144, v143
	v_fma_f32 v163, -v131, v162, v144
	v_fmac_f32_e32 v162, v163, v143
	v_fma_f32 v131, -v131, v162, v144
	v_div_fmas_f32 v131, v131, v143, v162
	v_div_fixup_f32 v141, v131, v141, 1.0
	v_div_scale_f32 v131, s[30:31], v140, v140, 1.0
	v_rcp_f32_e32 v143, v131
	s_nop 0
	v_fma_f32 v144, -v131, v143, 1.0
	v_fmac_f32_e32 v143, v144, v143
	v_div_scale_f32 v144, vcc, 1.0, v140, 1.0
	v_mul_f32_e32 v162, v144, v143
	v_fma_f32 v163, -v131, v162, v144
	v_fmac_f32_e32 v162, v163, v143
	v_fma_f32 v131, -v131, v162, v144
	v_div_fmas_f32 v131, v131, v143, v162
	v_div_fixup_f32 v140, v131, v140, 1.0
	v_mul_f32_e32 v131, 0xbfb8aa3b, v145
	v_exp_f32_e32 v143, v131
	v_pk_mul_f32 v[140:141], v[128:129], v[140:141]
	v_pk_add_f32 v[142:143], v[142:143], 1.0 op_sel_hi:[1,0]
	s_nop 0
	v_div_scale_f32 v131, s[30:31], v143, v143, 1.0
	v_rcp_f32_e32 v144, v131
	v_cvt_pk_bf16_f32 v137, v140, v141
	v_fma_f32 v145, -v131, v144, 1.0
	v_fmac_f32_e32 v144, v145, v144
	v_div_scale_f32 v145, vcc, 1.0, v143, 1.0
	v_mul_f32_e32 v162, v145, v144
	v_fma_f32 v163, -v131, v162, v145
	v_fmac_f32_e32 v162, v163, v144
	v_fma_f32 v131, -v131, v162, v145
	v_div_fmas_f32 v131, v131, v144, v162
	v_div_fixup_f32 v143, v131, v143, 1.0
	v_div_scale_f32 v131, s[30:31], v142, v142, 1.0
	v_rcp_f32_e32 v144, v131
	s_nop 0
	v_fma_f32 v145, -v131, v144, 1.0
	v_fmac_f32_e32 v144, v145, v144
	v_div_scale_f32 v145, vcc, 1.0, v142, 1.0
	v_mul_f32_e32 v162, v145, v144
	v_fma_f32 v163, -v131, v162, v145
	v_fmac_f32_e32 v162, v163, v144
	v_fma_f32 v131, -v131, v162, v145
	v_div_fmas_f32 v131, v131, v144, v162
	v_div_fixup_f32 v142, v131, v142, 1.0
	v_pk_mul_f32 v[142:143], v[116:117], v[142:143]
	s_nop 0
	v_cvt_pk_bf16_f32 v139, v142, v143
	global_store_dwordx4 v[134:135], v[136:139], off offset:256
	global_load_dwordx4 v[168:171], v[250:251], off offset:1088
	global_load_dwordx4 v[172:175], v[250:251], off offset:1344
	s_nop 1
	v_or_b32_e32 v136, 16, v130
	v_ashrrev_i32_e32 v137, 31, v136
	v_lshlrev_b64 v[134:135], 12, v[136:137]
	v_mad_i64_i32 v[136:137], s[30:31], v136, s79, v[132:133]
	v_lshl_add_u64 v[136:137], v[136:137], 0, s[28:29]
	v_lshl_add_u64 v[138:139], v[136:137], 0, v[0:1]
	v_lshl_add_u64 v[136:137], v[138:139], 0, s[60:61]
	v_add_co_u32_e32 v138, vcc, s17, v138
	v_lshl_add_u64 v[134:135], s[26:27], 0, v[134:135]
	s_nop 0
	v_addc_co_u32_e32 v139, vcc, 0, v139, vcc
	v_lshl_add_u64 v[134:135], v[134:135], 0, v[0:1]
	s_waitcnt vmcnt(15)
; __device__ __forceinline__ unsigned pk2(float lo, float hi) { return pg8::cvt_pk_bf16(lo, hi); }
; __device__ __forceinline__ float sigmoidf_(float x) { return 1.f / (1.f + __expf(-x)); }
;     __device__ __forceinline__ void operator()(const f32x4 (&acc)[2][2][4][2], const pg8::Unit& u, int wr, int wc, int fr, int fq) const {
;     ...
;                     const u32x4 gw = *(const u32x4*)(P + (size_t)row * NINP + GATEOFF + (gi - 1) * 2048 + col); float gt[8]; unpack8(gw, gt);
;                     const f32x4 v0 = acc[ai][bj][m][0], v1 = acc[ai][bj][m][1];
;                     float o[8];
; #pragma unroll
;                     for (int j = 0; j < 4; ++j) { o[j] = sigmoidf_(gt[j]) * v0[j]; o[4 + j] = sigmoidf_(gt[4 + j]) * v1[j]; }
;                     u32x4 w; w.x = pk2(o[0], o[1]); w.y = pk2(o[2], o[3]); w.z = pk2(o[4], o[5]); w.w = pk2(o[6], o[7]);
;                     *(u32x4*)(br + (size_t)row * D + col) = w; } }
	s_nop 1
	v_mov_b32_e32 v138, v176
	v_mov_b32_e32 v139, v177
	v_mov_b32_e32 v140, v178
	v_mov_b32_e32 v141, v179
	v_lshlrev_b32_e32 v131, 16, v138
	v_lshlrev_b32_e32 v143, 16, v139
	v_and_b32_e32 v145, 0xffff0000, v139
	v_lshlrev_b32_e32 v139, 16, v140
	v_mul_f32_e32 v131, 0xbfb8aa3b, v131
	v_and_b32_e32 v142, 0xffff0000, v138
	v_exp_f32_e32 v138, v131
	v_mul_f32_e32 v131, 0xbfb8aa3b, v139
	v_and_b32_e32 v144, 0xffff0000, v140
	v_exp_f32_e32 v140, v131
	v_mul_f32_e32 v131, 0xbfb8aa3b, v142
	v_exp_f32_e32 v139, v131
	v_lshlrev_b32_e32 v162, 16, v141
	v_and_b32_e32 v163, 0xffff0000, v141
	v_pk_add_f32 v[138:139], v[138:139], 1.0 op_sel_hi:[1,0]
	s_nop 0
	v_div_scale_f32 v131, s[30:31], v139, v139, 1.0
	v_rcp_f32_e32 v141, v131
	s_nop 0
	v_fma_f32 v142, -v131, v141, 1.0
	v_fmac_f32_e32 v141, v142, v141
	v_div_scale_f32 v142, vcc, 1.0, v139, 1.0
	v_mul_f32_e32 v164, v142, v141
	v_fma_f32 v165, -v131, v164, v142
	v_fmac_f32_e32 v164, v165, v141
	v_fma_f32 v131, -v131, v164, v142
	v_div_fmas_f32 v131, v131, v141, v164
	v_div_fixup_f32 v139, v131, v139, 1.0
	v_div_scale_f32 v131, s[30:31], v138, v138, 1.0
	v_rcp_f32_e32 v141, v131
	s_nop 0
	v_fma_f32 v142, -v131, v141, 1.0
	v_fmac_f32_e32 v141, v142, v141
	v_div_scale_f32 v142, vcc, 1.0, v138, 1.0
	v_mul_f32_e32 v164, v142, v141
	v_fma_f32 v165, -v131, v164, v142
	v_fmac_f32_e32 v164, v165, v141
	v_fma_f32 v131, -v131, v164, v142
	v_div_fmas_f32 v131, v131, v141, v164
	v_div_fixup_f32 v138, v131, v138, 1.0
	v_mul_f32_e32 v131, 0xbfb8aa3b, v144
	v_exp_f32_e32 v141, v131
	v_pk_mul_f32 v[138:139], v[110:111], v[138:139]
	v_pk_add_f32 v[140:141], v[140:141], 1.0 op_sel_hi:[1,0]
	s_nop 0
	v_div_scale_f32 v131, s[30:31], v141, v141, 1.0
	v_rcp_f32_e32 v142, v131
	v_cvt_pk_bf16_f32 v138, v138, v139
	v_fma_f32 v144, -v131, v142, 1.0
	v_fmac_f32_e32 v142, v144, v142
	v_div_scale_f32 v144, vcc, 1.0, v141, 1.0
	v_mul_f32_e32 v164, v144, v142
	v_fma_f32 v165, -v131, v164, v144
	v_fmac_f32_e32 v164, v165, v142
	v_fma_f32 v131, -v131, v164, v144
	v_div_fmas_f32 v131, v131, v142, v164
	v_div_fixup_f32 v141, v131, v141, 1.0
	v_div_scale_f32 v131, s[30:31], v140, v140, 1.0
	v_rcp_f32_e32 v142, v131
	s_nop 0
	v_fma_f32 v144, -v131, v142, 1.0
	v_fmac_f32_e32 v142, v144, v142
	v_div_scale_f32 v144, vcc, 1.0, v140, 1.0
	v_mul_f32_e32 v164, v144, v142
	v_fma_f32 v165, -v131, v164, v144
	v_fmac_f32_e32 v164, v165, v142
	v_fma_f32 v131, -v131, v164, v144
	v_div_fmas_f32 v131, v131, v142, v164
	v_div_fixup_f32 v140, v131, v140, 1.0
	v_mul_f32_e32 v131, 0xbfb8aa3b, v143
	v_exp_f32_e32 v142, v131
	v_mul_f32_e32 v131, 0xbfb8aa3b, v162
	v_exp_f32_e32 v144, v131
	v_mul_f32_e32 v131, 0xbfb8aa3b, v145
	v_exp_f32_e32 v143, v131
	v_pk_mul_f32 v[140:141], v[102:103], v[140:141]
	v_pk_add_f32 v[142:143], v[142:143], 1.0 op_sel_hi:[1,0]
	s_nop 0
	v_div_scale_f32 v131, s[30:31], v143, v143, 1.0
	v_rcp_f32_e32 v145, v131
	v_cvt_pk_bf16_f32 v140, v140, v141
	v_fma_f32 v162, -v131, v145, 1.0
	v_fmac_f32_e32 v145, v162, v145
	v_div_scale_f32 v162, vcc, 1.0, v143, 1.0
	v_mul_f32_e32 v164, v162, v145
	v_fma_f32 v165, -v131, v164, v162
	v_fmac_f32_e32 v164, v165, v145
	v_fma_f32 v131, -v131, v164, v162
	v_div_fmas_f32 v131, v131, v145, v164
	v_div_fixup_f32 v143, v131, v143, 1.0
	v_div_scale_f32 v131, s[30:31], v142, v142, 1.0
	v_rcp_f32_e32 v145, v131
	s_nop 0
	v_fma_f32 v162, -v131, v145, 1.0
	v_fmac_f32_e32 v145, v162, v145
	v_div_scale_f32 v162, vcc, 1.0, v142, 1.0
	v_mul_f32_e32 v164, v162, v145
	v_fma_f32 v165, -v131, v164, v162
	v_fmac_f32_e32 v164, v165, v145
	v_fma_f32 v131, -v131, v164, v162
	v_div_fmas_f32 v131, v131, v145, v164
	v_div_fixup_f32 v142, v131, v142, 1.0
	v_mul_f32_e32 v131, 0xbfb8aa3b, v163
	v_exp_f32_e32 v145, v131
	v_pk_mul_f32 v[142:143], v[112:113], v[142:143]
	v_pk_add_f32 v[144:145], v[144:145], 1.0 op_sel_hi:[1,0]
	s_nop 0
	v_div_scale_f32 v131, s[30:31], v145, v145, 1.0
	v_rcp_f32_e32 v162, v131
	v_cvt_pk_bf16_f32 v139, v142, v143
	v_fma_f32 v163, -v131, v162, 1.0
	v_fmac_f32_e32 v162, v163, v162
	v_div_scale_f32 v163, vcc, 1.0, v145, 1.0
	v_mul_f32_e32 v164, v163, v162
	v_fma_f32 v165, -v131, v164, v163
	v_fmac_f32_e32 v164, v165, v162
	v_fma_f32 v131, -v131, v164, v163
	v_div_fmas_f32 v131, v131, v162, v164
	v_div_fixup_f32 v145, v131, v145, 1.0
	v_div_scale_f32 v131, s[30:31], v144, v144, 1.0
	v_rcp_f32_e32 v162, v131
	s_nop 0
	v_fma_f32 v163, -v131, v162, 1.0
	v_fmac_f32_e32 v162, v163, v162
	v_div_scale_f32 v163, vcc, 1.0, v144, 1.0
	v_mul_f32_e32 v164, v163, v162
	v_fma_f32 v165, -v131, v164, v163
	v_fmac_f32_e32 v164, v165, v162
	v_fma_f32 v131, -v131, v164, v163
	v_div_fmas_f32 v131, v131, v162, v164
	v_div_fixup_f32 v144, v131, v144, 1.0
	v_pk_mul_f32 v[144:145], v[104:105], v[144:145]
	s_nop 0
	v_cvt_pk_bf16_f32 v141, v144, v145
	global_store_dwordx4 v[134:135], v[138:141], off
	s_waitcnt vmcnt(15)
; __device__ __forceinline__ unsigned pk2(float lo, float hi) { return pg8::cvt_pk_bf16(lo, hi); }
; __device__ __forceinline__ float sigmoidf_(float x) { return 1.f / (1.f + __expf(-x)); }
;     __device__ __forceinline__ void operator()(const f32x4 (&acc)[2][2][4][2], const pg8::Unit& u, int wr, int wc, int fr, int fq) const {
;     ...
;                     const u32x4 gw = *(const u32x4*)(P + (size_t)row * NINP + GATEOFF + (gi - 1) * 2048 + col); float gt[8]; unpack8(gw, gt);
;                     const f32x4 v0 = acc[ai][bj][m][0], v1 = acc[ai][bj][m][1];
;                     float o[8];
; #pragma unroll
;                     for (int j = 0; j < 4; ++j) { o[j] = sigmoidf_(gt[j]) * v0[j]; o[4 + j] = sigmoidf_(gt[4 + j]) * v1[j]; }
;                     u32x4 w; w.x = pk2(o[0], o[1]); w.y = pk2(o[2], o[3]); w.z = pk2(o[4], o[5]); w.w = pk2(o[6], o[7]);
;                     *(u32x4*)(br + (size_t)row * D + col) = w; } }
	s_nop 1
	v_mov_b32_e32 v136, v180
	v_mov_b32_e32 v137, v181
	v_mov_b32_e32 v138, v182
	v_mov_b32_e32 v139, v183
	v_lshlrev_b32_e32 v131, 16, v136
	v_lshlrev_b32_e32 v141, 16, v137
	v_and_b32_e32 v143, 0xffff0000, v137
	v_lshlrev_b32_e32 v137, 16, v138
	v_mul_f32_e32 v131, 0xbfb8aa3b, v131
	v_and_b32_e32 v140, 0xffff0000, v136
	v_exp_f32_e32 v136, v131
	v_mul_f32_e32 v131, 0xbfb8aa3b, v137
	v_and_b32_e32 v142, 0xffff0000, v138
	v_exp_f32_e32 v138, v131
	v_mul_f32_e32 v131, 0xbfb8aa3b, v140
	v_exp_f32_e32 v137, v131
	v_lshlrev_b32_e32 v144, 16, v139
	v_and_b32_e32 v145, 0xffff0000, v139
	v_pk_add_f32 v[136:137], v[136:137], 1.0 op_sel_hi:[1,0]
	s_nop 0
	v_div_scale_f32 v131, s[30:31], v137, v137, 1.0
	v_rcp_f32_e32 v139, v131
	s_nop 0
	v_fma_f32 v140, -v131, v139, 1.0
	v_fmac_f32_e32 v139, v140, v139
	v_div_scale_f32 v140, vcc, 1.0, v137, 1.0
	v_mul_f32_e32 v162, v140, v139
	v_fma_f32 v163, -v131, v162, v140
	v_fmac_f32_e32 v162, v163, v139
	v_fma_f32 v131, -v131, v162, v140
	v_div_fmas_f32 v131, v131, v139, v162
	v_div_fixup_f32 v137, v131, v137, 1.0
	v_div_scale_f32 v131, s[30:31], v136, v136, 1.0
	v_rcp_f32_e32 v139, v131
	s_nop 0
	v_fma_f32 v140, -v131, v139, 1.0
	v_fmac_f32_e32 v139, v140, v139
	v_div_scale_f32 v140, vcc, 1.0, v136, 1.0
	v_mul_f32_e32 v162, v140, v139
	v_fma_f32 v163, -v131, v162, v140
	v_fmac_f32_e32 v162, v163, v139
	v_fma_f32 v131, -v131, v162, v140
	v_div_fmas_f32 v131, v131, v139, v162
	v_div_fixup_f32 v136, v131, v136, 1.0
	v_mul_f32_e32 v131, 0xbfb8aa3b, v142
	v_exp_f32_e32 v139, v131
	v_pk_mul_f32 v[136:137], v[106:107], v[136:137]
	v_pk_add_f32 v[138:139], v[138:139], 1.0 op_sel_hi:[1,0]
	s_nop 0
	v_div_scale_f32 v131, s[30:31], v139, v139, 1.0
	v_rcp_f32_e32 v140, v131
	v_cvt_pk_bf16_f32 v136, v136, v137
	v_fma_f32 v142, -v131, v140, 1.0
	v_fmac_f32_e32 v140, v142, v140
	v_div_scale_f32 v142, vcc, 1.0, v139, 1.0
	v_mul_f32_e32 v162, v142, v140
	v_fma_f32 v163, -v131, v162, v142
	v_fmac_f32_e32 v162, v163, v140
	v_fma_f32 v131, -v131, v162, v142
	v_div_fmas_f32 v131, v131, v140, v162
	v_div_fixup_f32 v139, v131, v139, 1.0
	v_div_scale_f32 v131, s[30:31], v138, v138, 1.0
	v_rcp_f32_e32 v140, v131
	s_nop 0
	v_fma_f32 v142, -v131, v140, 1.0
	v_fmac_f32_e32 v140, v142, v140
	v_div_scale_f32 v142, vcc, 1.0, v138, 1.0
	v_mul_f32_e32 v162, v142, v140
	v_fma_f32 v163, -v131, v162, v142
	v_fmac_f32_e32 v162, v163, v140
	v_fma_f32 v131, -v131, v162, v142
	v_div_fmas_f32 v131, v131, v140, v162
	v_div_fixup_f32 v138, v131, v138, 1.0
	v_mul_f32_e32 v131, 0xbfb8aa3b, v141
	v_exp_f32_e32 v140, v131
	v_mul_f32_e32 v131, 0xbfb8aa3b, v144
	v_exp_f32_e32 v142, v131
	v_mul_f32_e32 v131, 0xbfb8aa3b, v143
	v_exp_f32_e32 v141, v131
	v_pk_mul_f32 v[138:139], v[98:99], v[138:139]
	v_pk_add_f32 v[140:141], v[140:141], 1.0 op_sel_hi:[1,0]
	s_nop 0
	v_div_scale_f32 v131, s[30:31], v141, v141, 1.0
	v_rcp_f32_e32 v143, v131
	v_cvt_pk_bf16_f32 v138, v138, v139
	v_fma_f32 v144, -v131, v143, 1.0
	v_fmac_f32_e32 v143, v144, v143
	v_div_scale_f32 v144, vcc, 1.0, v141, 1.0
	v_mul_f32_e32 v162, v144, v143
	v_fma_f32 v163, -v131, v162, v144
	v_fmac_f32_e32 v162, v163, v143
	v_fma_f32 v131, -v131, v162, v144
	v_div_fmas_f32 v131, v131, v143, v162
	v_div_fixup_f32 v141, v131, v141, 1.0
	v_div_scale_f32 v131, s[30:31], v140, v140, 1.0
	v_rcp_f32_e32 v143, v131
	s_nop 0
	v_fma_f32 v144, -v131, v143, 1.0
	v_fmac_f32_e32 v143, v144, v143
	v_div_scale_f32 v144, vcc, 1.0, v140, 1.0
	v_mul_f32_e32 v162, v144, v143
	v_fma_f32 v163, -v131, v162, v144
	v_fmac_f32_e32 v162, v163, v143
	v_fma_f32 v131, -v131, v162, v144
	v_div_fmas_f32 v131, v131, v143, v162
	v_div_fixup_f32 v140, v131, v140, 1.0
	v_mul_f32_e32 v131, 0xbfb8aa3b, v145
	v_exp_f32_e32 v143, v131
	v_pk_mul_f32 v[140:141], v[108:109], v[140:141]
	v_pk_add_f32 v[142:143], v[142:143], 1.0 op_sel_hi:[1,0]
	s_nop 0
	v_div_scale_f32 v131, s[30:31], v143, v143, 1.0
	v_rcp_f32_e32 v144, v131
	v_cvt_pk_bf16_f32 v137, v140, v141
	v_fma_f32 v145, -v131, v144, 1.0
	v_fmac_f32_e32 v144, v145, v144
	v_div_scale_f32 v145, vcc, 1.0, v143, 1.0
	v_mul_f32_e32 v162, v145, v144
	v_fma_f32 v163, -v131, v162, v145
	v_fmac_f32_e32 v162, v163, v144
	v_fma_f32 v131, -v131, v162, v145
	v_div_fmas_f32 v131, v131, v144, v162
	v_div_fixup_f32 v143, v131, v143, 1.0
	v_div_scale_f32 v131, s[30:31], v142, v142, 1.0
	v_rcp_f32_e32 v144, v131
	s_nop 0
	v_fma_f32 v145, -v131, v144, 1.0
	v_fmac_f32_e32 v144, v145, v144
	v_div_scale_f32 v145, vcc, 1.0, v142, 1.0
	v_mul_f32_e32 v162, v145, v144
	v_fma_f32 v163, -v131, v162, v145
	v_fmac_f32_e32 v162, v163, v144
	v_fma_f32 v131, -v131, v162, v145
	v_div_fmas_f32 v131, v131, v144, v162
	v_div_fixup_f32 v142, v131, v142, 1.0
	v_pk_mul_f32 v[142:143], v[100:101], v[142:143]
	s_nop 0
	v_cvt_pk_bf16_f32 v139, v142, v143
	global_store_dwordx4 v[134:135], v[136:139], off offset:256
	s_nop 1
	v_or_b32_e32 v136, 32, v130
	v_ashrrev_i32_e32 v137, 31, v136
	v_lshlrev_b64 v[134:135], 12, v[136:137]
	v_mad_i64_i32 v[136:137], s[30:31], v136, s79, v[132:133]
	v_lshl_add_u64 v[136:137], v[136:137], 0, s[28:29]
	v_lshl_add_u64 v[138:139], v[136:137], 0, v[0:1]
	v_lshl_add_u64 v[136:137], v[138:139], 0, s[60:61]
	v_add_co_u32_e32 v138, vcc, s17, v138
	v_lshl_add_u64 v[134:135], s[26:27], 0, v[134:135]
	s_nop 0
	v_addc_co_u32_e32 v139, vcc, 0, v139, vcc
	v_lshl_add_u64 v[134:135], v[134:135], 0, v[0:1]
	s_waitcnt vmcnt(15)
; __device__ __forceinline__ unsigned pk2(float lo, float hi) { return pg8::cvt_pk_bf16(lo, hi); }
; __device__ __forceinline__ float sigmoidf_(float x) { return 1.f / (1.f + __expf(-x)); }
;     __device__ __forceinline__ void operator()(const f32x4 (&acc)[2][2][4][2], const pg8::Unit& u, int wr, int wc, int fr, int fq) const {
;     ...
;                     const u32x4 gw = *(const u32x4*)(P + (size_t)row * NINP + GATEOFF + (gi - 1) * 2048 + col); float gt[8]; unpack8(gw, gt);
;                     const f32x4 v0 = acc[ai][bj][m][0], v1 = acc[ai][bj][m][1];
;                     float o[8];
; #pragma unroll
;                     for (int j = 0; j < 4; ++j) { o[j] = sigmoidf_(gt[j]) * v0[j]; o[4 + j] = sigmoidf_(gt[4 + j]) * v1[j]; }
;                     u32x4 w; w.x = pk2(o[0], o[1]); w.y = pk2(o[2], o[3]); w.z = pk2(o[4], o[5]); w.w = pk2(o[6], o[7]);
;                     *(u32x4*)(br + (size_t)row * D + col) = w; } }
	s_nop 1
	v_mov_b32_e32 v138, v184
	v_mov_b32_e32 v139, v185
	v_mov_b32_e32 v140, v186
	v_mov_b32_e32 v141, v187
	v_lshlrev_b32_e32 v131, 16, v138
	v_lshlrev_b32_e32 v143, 16, v139
	v_and_b32_e32 v145, 0xffff0000, v139
	v_lshlrev_b32_e32 v139, 16, v140
	v_mul_f32_e32 v131, 0xbfb8aa3b, v131
	v_and_b32_e32 v142, 0xffff0000, v138
	v_exp_f32_e32 v138, v131
	v_mul_f32_e32 v131, 0xbfb8aa3b, v139
	v_and_b32_e32 v144, 0xffff0000, v140
	v_exp_f32_e32 v140, v131
	v_mul_f32_e32 v131, 0xbfb8aa3b, v142
	v_exp_f32_e32 v139, v131
	v_lshlrev_b32_e32 v162, 16, v141
	v_and_b32_e32 v163, 0xffff0000, v141
	v_pk_add_f32 v[138:139], v[138:139], 1.0 op_sel_hi:[1,0]
	s_nop 0
	v_div_scale_f32 v131, s[30:31], v139, v139, 1.0
	v_rcp_f32_e32 v141, v131
	s_nop 0
	v_fma_f32 v142, -v131, v141, 1.0
	v_fmac_f32_e32 v141, v142, v141
	v_div_scale_f32 v142, vcc, 1.0, v139, 1.0
	v_mul_f32_e32 v164, v142, v141
	v_fma_f32 v165, -v131, v164, v142
	v_fmac_f32_e32 v164, v165, v141
	v_fma_f32 v131, -v131, v164, v142
	v_div_fmas_f32 v131, v131, v141, v164
	v_div_fixup_f32 v139, v131, v139, 1.0
	v_div_scale_f32 v131, s[30:31], v138, v138, 1.0
	v_rcp_f32_e32 v141, v131
	s_nop 0
	v_fma_f32 v142, -v131, v141, 1.0
	v_fmac_f32_e32 v141, v142, v141
	v_div_scale_f32 v142, vcc, 1.0, v138, 1.0
	v_mul_f32_e32 v164, v142, v141
	v_fma_f32 v165, -v131, v164, v142
	v_fmac_f32_e32 v164, v165, v141
	v_fma_f32 v131, -v131, v164, v142
	v_div_fmas_f32 v131, v131, v141, v164
	v_div_fixup_f32 v138, v131, v138, 1.0
	v_mul_f32_e32 v131, 0xbfb8aa3b, v144
	v_exp_f32_e32 v141, v131
	v_pk_mul_f32 v[138:139], v[94:95], v[138:139]
	v_pk_add_f32 v[140:141], v[140:141], 1.0 op_sel_hi:[1,0]
	s_nop 0
	v_div_scale_f32 v131, s[30:31], v141, v141, 1.0
	v_rcp_f32_e32 v142, v131
	v_cvt_pk_bf16_f32 v138, v138, v139
	v_fma_f32 v144, -v131, v142, 1.0
	v_fmac_f32_e32 v142, v144, v142
	v_div_scale_f32 v144, vcc, 1.0, v141, 1.0
	v_mul_f32_e32 v164, v144, v142
	v_fma_f32 v165, -v131, v164, v144
	v_fmac_f32_e32 v164, v165, v142
	v_fma_f32 v131, -v131, v164, v144
	v_div_fmas_f32 v131, v131, v142, v164
	v_div_fixup_f32 v141, v131, v141, 1.0
	v_div_scale_f32 v131, s[30:31], v140, v140, 1.0
	v_rcp_f32_e32 v142, v131
	s_nop 0
	v_fma_f32 v144, -v131, v142, 1.0
	v_fmac_f32_e32 v142, v144, v142
	v_div_scale_f32 v144, vcc, 1.0, v140, 1.0
	v_mul_f32_e32 v164, v144, v142
	v_fma_f32 v165, -v131, v164, v144
	v_fmac_f32_e32 v164, v165, v142
	v_fma_f32 v131, -v131, v164, v144
	v_div_fmas_f32 v131, v131, v142, v164
	v_div_fixup_f32 v140, v131, v140, 1.0
	v_mul_f32_e32 v131, 0xbfb8aa3b, v143
	v_exp_f32_e32 v142, v131
	v_mul_f32_e32 v131, 0xbfb8aa3b, v162
	v_exp_f32_e32 v144, v131
	v_mul_f32_e32 v131, 0xbfb8aa3b, v145
	v_exp_f32_e32 v143, v131
	v_pk_mul_f32 v[140:141], v[86:87], v[140:141]
	v_pk_add_f32 v[142:143], v[142:143], 1.0 op_sel_hi:[1,0]
	s_nop 0
	v_div_scale_f32 v131, s[30:31], v143, v143, 1.0
	v_rcp_f32_e32 v145, v131
	v_cvt_pk_bf16_f32 v140, v140, v141
	v_fma_f32 v162, -v131, v145, 1.0
	v_fmac_f32_e32 v145, v162, v145
	v_div_scale_f32 v162, vcc, 1.0, v143, 1.0
	v_mul_f32_e32 v164, v162, v145
	v_fma_f32 v165, -v131, v164, v162
	v_fmac_f32_e32 v164, v165, v145
	v_fma_f32 v131, -v131, v164, v162
	v_div_fmas_f32 v131, v131, v145, v164
	v_div_fixup_f32 v143, v131, v143, 1.0
	v_div_scale_f32 v131, s[30:31], v142, v142, 1.0
	v_rcp_f32_e32 v145, v131
	s_nop 0
	v_fma_f32 v162, -v131, v145, 1.0
	v_fmac_f32_e32 v145, v162, v145
	v_div_scale_f32 v162, vcc, 1.0, v142, 1.0
	v_mul_f32_e32 v164, v162, v145
	v_fma_f32 v165, -v131, v164, v162
	v_fmac_f32_e32 v164, v165, v145
	v_fma_f32 v131, -v131, v164, v162
	v_div_fmas_f32 v131, v131, v145, v164
	v_div_fixup_f32 v142, v131, v142, 1.0
	v_mul_f32_e32 v131, 0xbfb8aa3b, v163
	v_exp_f32_e32 v145, v131
	v_pk_mul_f32 v[142:143], v[96:97], v[142:143]
	v_pk_add_f32 v[144:145], v[144:145], 1.0 op_sel_hi:[1,0]
	s_nop 0
	v_div_scale_f32 v131, s[30:31], v145, v145, 1.0
	v_rcp_f32_e32 v162, v131
	v_cvt_pk_bf16_f32 v139, v142, v143
	v_fma_f32 v163, -v131, v162, 1.0
	v_fmac_f32_e32 v162, v163, v162
	v_div_scale_f32 v163, vcc, 1.0, v145, 1.0
	v_mul_f32_e32 v164, v163, v162
	v_fma_f32 v165, -v131, v164, v163
	v_fmac_f32_e32 v164, v165, v162
	v_fma_f32 v131, -v131, v164, v163
	v_div_fmas_f32 v131, v131, v162, v164
	v_div_fixup_f32 v145, v131, v145, 1.0
	v_div_scale_f32 v131, s[30:31], v144, v144, 1.0
	v_rcp_f32_e32 v162, v131
	s_nop 0
	v_fma_f32 v163, -v131, v162, 1.0
	v_fmac_f32_e32 v162, v163, v162
	v_div_scale_f32 v163, vcc, 1.0, v144, 1.0
	v_mul_f32_e32 v164, v163, v162
	v_fma_f32 v165, -v131, v164, v163
	v_fmac_f32_e32 v164, v165, v162
	v_fma_f32 v131, -v131, v164, v163
	v_div_fmas_f32 v131, v131, v162, v164
	v_div_fixup_f32 v144, v131, v144, 1.0
	v_pk_mul_f32 v[144:145], v[88:89], v[144:145]
	s_nop 0
	v_cvt_pk_bf16_f32 v141, v144, v145
	global_store_dwordx4 v[134:135], v[138:141], off
	s_waitcnt vmcnt(15)
; __device__ __forceinline__ unsigned pk2(float lo, float hi) { return pg8::cvt_pk_bf16(lo, hi); }
; __device__ __forceinline__ float sigmoidf_(float x) { return 1.f / (1.f + __expf(-x)); }
;     __device__ __forceinline__ void operator()(const f32x4 (&acc)[2][2][4][2], const pg8::Unit& u, int wr, int wc, int fr, int fq) const {
;     ...
;                     const u32x4 gw = *(const u32x4*)(P + (size_t)row * NINP + GATEOFF + (gi - 1) * 2048 + col); float gt[8]; unpack8(gw, gt);
;                     const f32x4 v0 = acc[ai][bj][m][0], v1 = acc[ai][bj][m][1];
;                     float o[8];
; #pragma unroll
;                     for (int j = 0; j < 4; ++j) { o[j] = sigmoidf_(gt[j]) * v0[j]; o[4 + j] = sigmoidf_(gt[4 + j]) * v1[j]; }
;                     u32x4 w; w.x = pk2(o[0], o[1]); w.y = pk2(o[2], o[3]); w.z = pk2(o[4], o[5]); w.w = pk2(o[6], o[7]);
;                     *(u32x4*)(br + (size_t)row * D + col) = w; } }
	s_nop 1
	v_mov_b32_e32 v136, v214
	v_mov_b32_e32 v137, v215
	v_mov_b32_e32 v138, v216
	v_mov_b32_e32 v139, v217
	v_lshlrev_b32_e32 v131, 16, v136
	v_lshlrev_b32_e32 v141, 16, v137
	v_and_b32_e32 v143, 0xffff0000, v137
	v_lshlrev_b32_e32 v137, 16, v138
	v_mul_f32_e32 v131, 0xbfb8aa3b, v131
	v_and_b32_e32 v140, 0xffff0000, v136
	v_exp_f32_e32 v136, v131
	v_mul_f32_e32 v131, 0xbfb8aa3b, v137
	v_and_b32_e32 v142, 0xffff0000, v138
	v_exp_f32_e32 v138, v131
	v_mul_f32_e32 v131, 0xbfb8aa3b, v140
	v_exp_f32_e32 v137, v131
	v_lshlrev_b32_e32 v144, 16, v139
	v_and_b32_e32 v145, 0xffff0000, v139
	v_pk_add_f32 v[136:137], v[136:137], 1.0 op_sel_hi:[1,0]
	s_nop 0
	v_div_scale_f32 v131, s[30:31], v137, v137, 1.0
	v_rcp_f32_e32 v139, v131
	s_nop 0
	v_fma_f32 v140, -v131, v139, 1.0
	v_fmac_f32_e32 v139, v140, v139
	v_div_scale_f32 v140, vcc, 1.0, v137, 1.0
	v_mul_f32_e32 v162, v140, v139
	v_fma_f32 v163, -v131, v162, v140
	v_fmac_f32_e32 v162, v163, v139
	v_fma_f32 v131, -v131, v162, v140
	v_div_fmas_f32 v131, v131, v139, v162
	v_div_fixup_f32 v137, v131, v137, 1.0
	v_div_scale_f32 v131, s[30:31], v136, v136, 1.0
	v_rcp_f32_e32 v139, v131
	s_nop 0
	v_fma_f32 v140, -v131, v139, 1.0
	v_fmac_f32_e32 v139, v140, v139
	v_div_scale_f32 v140, vcc, 1.0, v136, 1.0
	v_mul_f32_e32 v162, v140, v139
	v_fma_f32 v163, -v131, v162, v140
	v_fmac_f32_e32 v162, v163, v139
	v_fma_f32 v131, -v131, v162, v140
	v_div_fmas_f32 v131, v131, v139, v162
	v_div_fixup_f32 v136, v131, v136, 1.0
	v_mul_f32_e32 v131, 0xbfb8aa3b, v142
	v_exp_f32_e32 v139, v131
	v_pk_mul_f32 v[136:137], v[90:91], v[136:137]
	v_pk_add_f32 v[138:139], v[138:139], 1.0 op_sel_hi:[1,0]
	s_nop 0
	v_div_scale_f32 v131, s[30:31], v139, v139, 1.0
	v_rcp_f32_e32 v140, v131
	v_cvt_pk_bf16_f32 v136, v136, v137
	v_fma_f32 v142, -v131, v140, 1.0
	v_fmac_f32_e32 v140, v142, v140
	v_div_scale_f32 v142, vcc, 1.0, v139, 1.0
	v_mul_f32_e32 v162, v142, v140
	v_fma_f32 v163, -v131, v162, v142
	v_fmac_f32_e32 v162, v163, v140
	v_fma_f32 v131, -v131, v162, v142
	v_div_fmas_f32 v131, v131, v140, v162
	v_div_fixup_f32 v139, v131, v139, 1.0
	v_div_scale_f32 v131, s[30:31], v138, v138, 1.0
	v_rcp_f32_e32 v140, v131
	s_nop 0
	v_fma_f32 v142, -v131, v140, 1.0
	v_fmac_f32_e32 v140, v142, v140
	v_div_scale_f32 v142, vcc, 1.0, v138, 1.0
	v_mul_f32_e32 v162, v142, v140
	v_fma_f32 v163, -v131, v162, v142
	v_fmac_f32_e32 v162, v163, v140
	v_fma_f32 v131, -v131, v162, v142
	v_div_fmas_f32 v131, v131, v140, v162
	v_div_fixup_f32 v138, v131, v138, 1.0
	v_mul_f32_e32 v131, 0xbfb8aa3b, v141
	v_exp_f32_e32 v140, v131
	v_mul_f32_e32 v131, 0xbfb8aa3b, v144
	v_exp_f32_e32 v142, v131
	v_mul_f32_e32 v131, 0xbfb8aa3b, v143
	v_exp_f32_e32 v141, v131
	v_pk_mul_f32 v[138:139], v[82:83], v[138:139]
	v_pk_add_f32 v[140:141], v[140:141], 1.0 op_sel_hi:[1,0]
	s_nop 0
	v_div_scale_f32 v131, s[30:31], v141, v141, 1.0
	v_rcp_f32_e32 v143, v131
	v_cvt_pk_bf16_f32 v138, v138, v139
	v_fma_f32 v144, -v131, v143, 1.0
	v_fmac_f32_e32 v143, v144, v143
	v_div_scale_f32 v144, vcc, 1.0, v141, 1.0
	v_mul_f32_e32 v162, v144, v143
	v_fma_f32 v163, -v131, v162, v144
	v_fmac_f32_e32 v162, v163, v143
	v_fma_f32 v131, -v131, v162, v144
	v_div_fmas_f32 v131, v131, v143, v162
	v_div_fixup_f32 v141, v131, v141, 1.0
	v_div_scale_f32 v131, s[30:31], v140, v140, 1.0
	v_rcp_f32_e32 v143, v131
	s_nop 0
	v_fma_f32 v144, -v131, v143, 1.0
	v_fmac_f32_e32 v143, v144, v143
	v_div_scale_f32 v144, vcc, 1.0, v140, 1.0
	v_mul_f32_e32 v162, v144, v143
	v_fma_f32 v163, -v131, v162, v144
	v_fmac_f32_e32 v162, v163, v143
	v_fma_f32 v131, -v131, v162, v144
	v_div_fmas_f32 v131, v131, v143, v162
	v_div_fixup_f32 v140, v131, v140, 1.0
	v_mul_f32_e32 v131, 0xbfb8aa3b, v145
	v_exp_f32_e32 v143, v131
	v_pk_mul_f32 v[140:141], v[92:93], v[140:141]
	v_pk_add_f32 v[142:143], v[142:143], 1.0 op_sel_hi:[1,0]
	s_nop 0
	v_div_scale_f32 v131, s[30:31], v143, v143, 1.0
	v_rcp_f32_e32 v144, v131
	v_cvt_pk_bf16_f32 v137, v140, v141
	v_fma_f32 v145, -v131, v144, 1.0
	v_fmac_f32_e32 v144, v145, v144
	v_div_scale_f32 v145, vcc, 1.0, v143, 1.0
	v_mul_f32_e32 v162, v145, v144
	v_fma_f32 v163, -v131, v162, v145
	v_fmac_f32_e32 v162, v163, v144
	v_fma_f32 v131, -v131, v162, v145
	v_div_fmas_f32 v131, v131, v144, v162
	v_div_fixup_f32 v143, v131, v143, 1.0
	v_div_scale_f32 v131, s[30:31], v142, v142, 1.0
	v_rcp_f32_e32 v144, v131
	s_nop 0
	v_fma_f32 v145, -v131, v144, 1.0
	v_fmac_f32_e32 v144, v145, v144
	v_div_scale_f32 v145, vcc, 1.0, v142, 1.0
	v_mul_f32_e32 v162, v145, v144
	v_fma_f32 v163, -v131, v162, v145
	v_fmac_f32_e32 v162, v163, v144
	v_fma_f32 v131, -v131, v162, v145
	v_div_fmas_f32 v131, v131, v144, v162
	v_div_fixup_f32 v142, v131, v142, 1.0
	v_pk_mul_f32 v[142:143], v[84:85], v[142:143]
	s_nop 0
	v_cvt_pk_bf16_f32 v139, v142, v143
	global_store_dwordx4 v[134:135], v[136:139], off offset:256
	s_nop 1
	v_or_b32_e32 v136, 48, v130
	v_ashrrev_i32_e32 v137, 31, v136
	v_lshlrev_b64 v[134:135], 12, v[136:137]
	v_mad_i64_i32 v[136:137], s[30:31], v136, s79, v[132:133]
	v_lshl_add_u64 v[136:137], v[136:137], 0, s[28:29]
	v_lshl_add_u64 v[138:139], v[136:137], 0, v[0:1]
	v_lshl_add_u64 v[136:137], v[138:139], 0, s[60:61]
	v_add_co_u32_e32 v138, vcc, s17, v138
	v_lshl_add_u64 v[134:135], s[26:27], 0, v[134:135]
	s_nop 0
	v_addc_co_u32_e32 v139, vcc, 0, v139, vcc
	v_lshl_add_u64 v[134:135], v[134:135], 0, v[0:1]
	s_waitcnt vmcnt(15)
; __device__ __forceinline__ unsigned pk2(float lo, float hi) { return pg8::cvt_pk_bf16(lo, hi); }
; __device__ __forceinline__ float sigmoidf_(float x) { return 1.f / (1.f + __expf(-x)); }
;     __device__ __forceinline__ void operator()(const f32x4 (&acc)[2][2][4][2], const pg8::Unit& u, int wr, int wc, int fr, int fq) const {
;     ...
;                     const u32x4 gw = *(const u32x4*)(P + (size_t)row * NINP + GATEOFF + (gi - 1) * 2048 + col); float gt[8]; unpack8(gw, gt);
;                     const f32x4 v0 = acc[ai][bj][m][0], v1 = acc[ai][bj][m][1];
;                     float o[8];
; #pragma unroll
;                     for (int j = 0; j < 4; ++j) { o[j] = sigmoidf_(gt[j]) * v0[j]; o[4 + j] = sigmoidf_(gt[4 + j]) * v1[j]; }
;                     u32x4 w; w.x = pk2(o[0], o[1]); w.y = pk2(o[2], o[3]); w.z = pk2(o[4], o[5]); w.w = pk2(o[6], o[7]);
;                     *(u32x4*)(br + (size_t)row * D + col) = w; } }
	s_nop 1
	v_mov_b32_e32 v138, v218
	v_mov_b32_e32 v139, v219
	v_mov_b32_e32 v140, v220
	v_mov_b32_e32 v141, v221
	v_lshlrev_b32_e32 v131, 16, v138
	v_lshlrev_b32_e32 v143, 16, v139
	v_and_b32_e32 v145, 0xffff0000, v139
	v_lshlrev_b32_e32 v139, 16, v140
	v_mul_f32_e32 v131, 0xbfb8aa3b, v131
	v_and_b32_e32 v142, 0xffff0000, v138
	v_exp_f32_e32 v138, v131
	v_mul_f32_e32 v131, 0xbfb8aa3b, v139
	v_and_b32_e32 v144, 0xffff0000, v140
	v_exp_f32_e32 v140, v131
	v_mul_f32_e32 v131, 0xbfb8aa3b, v142
	v_exp_f32_e32 v139, v131
	v_lshlrev_b32_e32 v162, 16, v141
	v_and_b32_e32 v163, 0xffff0000, v141
	v_pk_add_f32 v[138:139], v[138:139], 1.0 op_sel_hi:[1,0]
	s_nop 0
	v_div_scale_f32 v131, s[30:31], v139, v139, 1.0
	v_rcp_f32_e32 v141, v131
	s_nop 0
	v_fma_f32 v142, -v131, v141, 1.0
	v_fmac_f32_e32 v141, v142, v141
	v_div_scale_f32 v142, vcc, 1.0, v139, 1.0
	v_mul_f32_e32 v164, v142, v141
	v_fma_f32 v165, -v131, v164, v142
	v_fmac_f32_e32 v164, v165, v141
	v_fma_f32 v131, -v131, v164, v142
	v_div_fmas_f32 v131, v131, v141, v164
	v_div_fixup_f32 v139, v131, v139, 1.0
	v_div_scale_f32 v131, s[30:31], v138, v138, 1.0
	v_rcp_f32_e32 v141, v131
	s_nop 0
	v_fma_f32 v142, -v131, v141, 1.0
	v_fmac_f32_e32 v141, v142, v141
	v_div_scale_f32 v142, vcc, 1.0, v138, 1.0
	v_mul_f32_e32 v164, v142, v141
	v_fma_f32 v165, -v131, v164, v142
	v_fmac_f32_e32 v164, v165, v141
	v_fma_f32 v131, -v131, v164, v142
	v_div_fmas_f32 v131, v131, v141, v164
	v_div_fixup_f32 v138, v131, v138, 1.0
	v_mul_f32_e32 v131, 0xbfb8aa3b, v144
	v_exp_f32_e32 v141, v131
	v_pk_mul_f32 v[138:139], v[78:79], v[138:139]
	v_pk_add_f32 v[140:141], v[140:141], 1.0 op_sel_hi:[1,0]
	s_nop 0
	v_div_scale_f32 v131, s[30:31], v141, v141, 1.0
	v_rcp_f32_e32 v142, v131
	v_cvt_pk_bf16_f32 v138, v138, v139
	v_fma_f32 v144, -v131, v142, 1.0
	v_fmac_f32_e32 v142, v144, v142
	v_div_scale_f32 v144, vcc, 1.0, v141, 1.0
	v_mul_f32_e32 v164, v144, v142
	v_fma_f32 v165, -v131, v164, v144
	v_fmac_f32_e32 v164, v165, v142
	v_fma_f32 v131, -v131, v164, v144
	v_div_fmas_f32 v131, v131, v142, v164
	v_div_fixup_f32 v141, v131, v141, 1.0
	v_div_scale_f32 v131, s[30:31], v140, v140, 1.0
	v_rcp_f32_e32 v142, v131
	s_nop 0
	v_fma_f32 v144, -v131, v142, 1.0
	v_fmac_f32_e32 v142, v144, v142
	v_div_scale_f32 v144, vcc, 1.0, v140, 1.0
	v_mul_f32_e32 v164, v144, v142
	v_fma_f32 v165, -v131, v164, v144
	v_fmac_f32_e32 v164, v165, v142
	v_fma_f32 v131, -v131, v164, v144
	v_div_fmas_f32 v131, v131, v142, v164
	v_div_fixup_f32 v140, v131, v140, 1.0
	v_mul_f32_e32 v131, 0xbfb8aa3b, v143
	v_exp_f32_e32 v142, v131
	v_mul_f32_e32 v131, 0xbfb8aa3b, v162
	v_exp_f32_e32 v144, v131
	v_mul_f32_e32 v131, 0xbfb8aa3b, v145
	v_exp_f32_e32 v143, v131
	v_pk_mul_f32 v[140:141], v[70:71], v[140:141]
	v_pk_add_f32 v[142:143], v[142:143], 1.0 op_sel_hi:[1,0]
	s_nop 0
	v_div_scale_f32 v131, s[30:31], v143, v143, 1.0
	v_rcp_f32_e32 v145, v131
	v_cvt_pk_bf16_f32 v140, v140, v141
	v_fma_f32 v162, -v131, v145, 1.0
	v_fmac_f32_e32 v145, v162, v145
	v_div_scale_f32 v162, vcc, 1.0, v143, 1.0
	v_mul_f32_e32 v164, v162, v145
	v_fma_f32 v165, -v131, v164, v162
	v_fmac_f32_e32 v164, v165, v145
	v_fma_f32 v131, -v131, v164, v162
	v_div_fmas_f32 v131, v131, v145, v164
	v_div_fixup_f32 v143, v131, v143, 1.0
	v_div_scale_f32 v131, s[30:31], v142, v142, 1.0
	v_rcp_f32_e32 v145, v131
	s_nop 0
	v_fma_f32 v162, -v131, v145, 1.0
	v_fmac_f32_e32 v145, v162, v145
	v_div_scale_f32 v162, vcc, 1.0, v142, 1.0
	v_mul_f32_e32 v164, v162, v145
	v_fma_f32 v165, -v131, v164, v162
	v_fmac_f32_e32 v164, v165, v145
	v_fma_f32 v131, -v131, v164, v162
	v_div_fmas_f32 v131, v131, v145, v164
	v_div_fixup_f32 v142, v131, v142, 1.0
	v_mul_f32_e32 v131, 0xbfb8aa3b, v163
	v_exp_f32_e32 v145, v131
	v_pk_mul_f32 v[142:143], v[80:81], v[142:143]
	v_pk_add_f32 v[144:145], v[144:145], 1.0 op_sel_hi:[1,0]
	s_nop 0
	v_div_scale_f32 v131, s[30:31], v145, v145, 1.0
	v_rcp_f32_e32 v162, v131
	v_cvt_pk_bf16_f32 v139, v142, v143
	v_fma_f32 v163, -v131, v162, 1.0
	v_fmac_f32_e32 v162, v163, v162
	v_div_scale_f32 v163, vcc, 1.0, v145, 1.0
	v_mul_f32_e32 v164, v163, v162
	v_fma_f32 v165, -v131, v164, v163
	v_fmac_f32_e32 v164, v165, v162
	v_fma_f32 v131, -v131, v164, v163
	v_div_fmas_f32 v131, v131, v162, v164
	v_div_fixup_f32 v145, v131, v145, 1.0
	v_div_scale_f32 v131, s[30:31], v144, v144, 1.0
	v_rcp_f32_e32 v162, v131
	s_nop 0
	v_fma_f32 v163, -v131, v162, 1.0
	v_fmac_f32_e32 v162, v163, v162
	v_div_scale_f32 v163, vcc, 1.0, v144, 1.0
	v_mul_f32_e32 v164, v163, v162
	v_fma_f32 v165, -v131, v164, v163
	v_fmac_f32_e32 v164, v165, v162
	v_fma_f32 v131, -v131, v164, v163
	v_div_fmas_f32 v131, v131, v162, v164
	v_div_fixup_f32 v144, v131, v144, 1.0
	v_pk_mul_f32 v[144:145], v[72:73], v[144:145]
	s_nop 0
	v_cvt_pk_bf16_f32 v141, v144, v145
	global_store_dwordx4 v[134:135], v[138:141], off
	s_waitcnt vmcnt(15)
; __device__ __forceinline__ unsigned pk2(float lo, float hi) { return pg8::cvt_pk_bf16(lo, hi); }
; __device__ __forceinline__ float sigmoidf_(float x) { return 1.f / (1.f + __expf(-x)); }
;     __device__ __forceinline__ void operator()(const f32x4 (&acc)[2][2][4][2], const pg8::Unit& u, int wr, int wc, int fr, int fq) const {
;     ...
;                     const u32x4 gw = *(const u32x4*)(P + (size_t)row * NINP + GATEOFF + (gi - 1) * 2048 + col); float gt[8]; unpack8(gw, gt);
;                     const f32x4 v0 = acc[ai][bj][m][0], v1 = acc[ai][bj][m][1];
;                     float o[8];
; #pragma unroll
;                     for (int j = 0; j < 4; ++j) { o[j] = sigmoidf_(gt[j]) * v0[j]; o[4 + j] = sigmoidf_(gt[4 + j]) * v1[j]; }
;                     u32x4 w; w.x = pk2(o[0], o[1]); w.y = pk2(o[2], o[3]); w.z = pk2(o[4], o[5]); w.w = pk2(o[6], o[7]);
;                     *(u32x4*)(br + (size_t)row * D + col) = w; } }
	s_nop 1
	v_mov_b32_e32 v136, v222
	v_mov_b32_e32 v137, v223
	v_mov_b32_e32 v138, v224
	v_mov_b32_e32 v139, v225
	v_lshlrev_b32_e32 v131, 16, v136
	v_lshlrev_b32_e32 v141, 16, v137
	v_and_b32_e32 v143, 0xffff0000, v137
	v_lshlrev_b32_e32 v137, 16, v138
	v_mul_f32_e32 v131, 0xbfb8aa3b, v131
	v_and_b32_e32 v140, 0xffff0000, v136
	v_exp_f32_e32 v136, v131
	v_mul_f32_e32 v131, 0xbfb8aa3b, v137
	v_and_b32_e32 v142, 0xffff0000, v138
	v_exp_f32_e32 v138, v131
	v_mul_f32_e32 v131, 0xbfb8aa3b, v140
	v_exp_f32_e32 v137, v131
	v_lshlrev_b32_e32 v144, 16, v139
	v_and_b32_e32 v145, 0xffff0000, v139
	v_pk_add_f32 v[136:137], v[136:137], 1.0 op_sel_hi:[1,0]
	s_nop 0
	v_div_scale_f32 v131, s[30:31], v137, v137, 1.0
	v_rcp_f32_e32 v139, v131
	s_nop 0
	v_fma_f32 v140, -v131, v139, 1.0
	v_fmac_f32_e32 v139, v140, v139
	v_div_scale_f32 v140, vcc, 1.0, v137, 1.0
	v_mul_f32_e32 v162, v140, v139
	v_fma_f32 v163, -v131, v162, v140
	v_fmac_f32_e32 v162, v163, v139
	v_fma_f32 v131, -v131, v162, v140
	v_div_fmas_f32 v131, v131, v139, v162
	v_div_fixup_f32 v137, v131, v137, 1.0
	v_div_scale_f32 v131, s[30:31], v136, v136, 1.0
	v_rcp_f32_e32 v139, v131
	s_nop 0
	v_fma_f32 v140, -v131, v139, 1.0
	v_fmac_f32_e32 v139, v140, v139
	v_div_scale_f32 v140, vcc, 1.0, v136, 1.0
	v_mul_f32_e32 v162, v140, v139
	v_fma_f32 v163, -v131, v162, v140
	v_fmac_f32_e32 v162, v163, v139
	v_fma_f32 v131, -v131, v162, v140
	v_div_fmas_f32 v131, v131, v139, v162
	v_div_fixup_f32 v136, v131, v136, 1.0
	v_mul_f32_e32 v131, 0xbfb8aa3b, v142
	v_exp_f32_e32 v139, v131
	v_pk_mul_f32 v[136:137], v[74:75], v[136:137]
	v_pk_add_f32 v[138:139], v[138:139], 1.0 op_sel_hi:[1,0]
	s_nop 0
	v_div_scale_f32 v131, s[30:31], v139, v139, 1.0
	v_rcp_f32_e32 v140, v131
	v_cvt_pk_bf16_f32 v136, v136, v137
	v_fma_f32 v142, -v131, v140, 1.0
	v_fmac_f32_e32 v140, v142, v140
	v_div_scale_f32 v142, vcc, 1.0, v139, 1.0
	v_mul_f32_e32 v162, v142, v140
	v_fma_f32 v163, -v131, v162, v142
	v_fmac_f32_e32 v162, v163, v140
	v_fma_f32 v131, -v131, v162, v142
	v_div_fmas_f32 v131, v131, v140, v162
	v_div_fixup_f32 v139, v131, v139, 1.0
	v_div_scale_f32 v131, s[30:31], v138, v138, 1.0
	v_rcp_f32_e32 v140, v131
	s_nop 0
	v_fma_f32 v142, -v131, v140, 1.0
	v_fmac_f32_e32 v140, v142, v140
	v_div_scale_f32 v142, vcc, 1.0, v138, 1.0
	v_mul_f32_e32 v162, v142, v140
	v_fma_f32 v163, -v131, v162, v142
	v_fmac_f32_e32 v162, v163, v140
	v_fma_f32 v131, -v131, v162, v142
	v_div_fmas_f32 v131, v131, v140, v162
	v_div_fixup_f32 v138, v131, v138, 1.0
	v_mul_f32_e32 v131, 0xbfb8aa3b, v141
	v_exp_f32_e32 v140, v131
	v_mul_f32_e32 v131, 0xbfb8aa3b, v144
	v_exp_f32_e32 v142, v131
	v_mul_f32_e32 v131, 0xbfb8aa3b, v143
	v_exp_f32_e32 v141, v131
	v_pk_mul_f32 v[138:139], v[66:67], v[138:139]
	v_pk_add_f32 v[140:141], v[140:141], 1.0 op_sel_hi:[1,0]
	s_nop 0
	v_div_scale_f32 v131, s[30:31], v141, v141, 1.0
	v_rcp_f32_e32 v143, v131
	v_cvt_pk_bf16_f32 v138, v138, v139
	v_fma_f32 v144, -v131, v143, 1.0
	v_fmac_f32_e32 v143, v144, v143
	v_div_scale_f32 v144, vcc, 1.0, v141, 1.0
	v_mul_f32_e32 v162, v144, v143
	v_fma_f32 v163, -v131, v162, v144
	v_fmac_f32_e32 v162, v163, v143
	v_fma_f32 v131, -v131, v162, v144
	v_div_fmas_f32 v131, v131, v143, v162
	v_div_fixup_f32 v141, v131, v141, 1.0
	v_div_scale_f32 v131, s[30:31], v140, v140, 1.0
	v_rcp_f32_e32 v143, v131
	s_nop 0
	v_fma_f32 v144, -v131, v143, 1.0
	v_fmac_f32_e32 v143, v144, v143
	v_div_scale_f32 v144, vcc, 1.0, v140, 1.0
	v_mul_f32_e32 v162, v144, v143
	v_fma_f32 v163, -v131, v162, v144
	v_fmac_f32_e32 v162, v163, v143
	v_fma_f32 v131, -v131, v162, v144
	v_div_fmas_f32 v131, v131, v143, v162
	v_div_fixup_f32 v140, v131, v140, 1.0
	v_mul_f32_e32 v131, 0xbfb8aa3b, v145
	v_exp_f32_e32 v143, v131
	v_pk_mul_f32 v[140:141], v[76:77], v[140:141]
	v_pk_add_f32 v[142:143], v[142:143], 1.0 op_sel_hi:[1,0]
	s_nop 0
	v_div_scale_f32 v131, s[30:31], v143, v143, 1.0
	v_rcp_f32_e32 v144, v131
	v_cvt_pk_bf16_f32 v137, v140, v141
	v_fma_f32 v145, -v131, v144, 1.0
	v_fmac_f32_e32 v144, v145, v144
	v_div_scale_f32 v145, vcc, 1.0, v143, 1.0
	v_mul_f32_e32 v162, v145, v144
	v_fma_f32 v163, -v131, v162, v145
	v_fmac_f32_e32 v162, v163, v144
	v_fma_f32 v131, -v131, v162, v145
	v_div_fmas_f32 v131, v131, v144, v162
	v_div_fixup_f32 v143, v131, v143, 1.0
	v_div_scale_f32 v131, s[30:31], v142, v142, 1.0
	v_rcp_f32_e32 v144, v131
	s_nop 0
	v_fma_f32 v145, -v131, v144, 1.0
	v_fmac_f32_e32 v144, v145, v144
	v_div_scale_f32 v145, vcc, 1.0, v142, 1.0
	v_mul_f32_e32 v162, v145, v144
	v_fma_f32 v163, -v131, v162, v145
	v_fmac_f32_e32 v162, v163, v144
	v_fma_f32 v131, -v131, v162, v145
	v_div_fmas_f32 v131, v131, v144, v162
	v_div_fixup_f32 v142, v131, v142, 1.0
	v_pk_mul_f32 v[142:143], v[68:69], v[142:143]
	s_nop 0
	v_cvt_pk_bf16_f32 v139, v142, v143
	global_store_dwordx4 v[134:135], v[136:139], off offset:256
	s_nop 1
	v_add_u32_e32 v136, 0x80, v130
	v_ashrrev_i32_e32 v137, 31, v136
	v_lshlrev_b64 v[134:135], 12, v[136:137]
	v_mad_i64_i32 v[136:137], s[30:31], v136, s79, v[132:133]
	v_lshl_add_u64 v[136:137], v[136:137], 0, s[28:29]
	v_lshl_add_u64 v[138:139], v[136:137], 0, v[0:1]
	v_lshl_add_u64 v[136:137], v[138:139], 0, s[60:61]
	v_add_co_u32_e32 v138, vcc, s17, v138
	v_lshl_add_u64 v[134:135], s[26:27], 0, v[134:135]
	s_nop 0
	v_addc_co_u32_e32 v139, vcc, 0, v139, vcc
	v_lshl_add_u64 v[134:135], v[134:135], 0, v[0:1]
	s_waitcnt vmcnt(15)
; __device__ __forceinline__ unsigned pk2(float lo, float hi) { return pg8::cvt_pk_bf16(lo, hi); }
; __device__ __forceinline__ float sigmoidf_(float x) { return 1.f / (1.f + __expf(-x)); }
;     __device__ __forceinline__ void operator()(const f32x4 (&acc)[2][2][4][2], const pg8::Unit& u, int wr, int wc, int fr, int fq) const {
;     ...
;                     const u32x4 gw = *(const u32x4*)(P + (size_t)row * NINP + GATEOFF + (gi - 1) * 2048 + col); float gt[8]; unpack8(gw, gt);
;                     const f32x4 v0 = acc[ai][bj][m][0], v1 = acc[ai][bj][m][1];
;                     float o[8];
; #pragma unroll
;                     for (int j = 0; j < 4; ++j) { o[j] = sigmoidf_(gt[j]) * v0[j]; o[4 + j] = sigmoidf_(gt[4 + j]) * v1[j]; }
;                     u32x4 w; w.x = pk2(o[0], o[1]); w.y = pk2(o[2], o[3]); w.z = pk2(o[4], o[5]); w.w = pk2(o[6], o[7]);
;                     *(u32x4*)(br + (size_t)row * D + col) = w; } }
	s_nop 1
	v_mov_b32_e32 v138, v226
	v_mov_b32_e32 v139, v227
	v_mov_b32_e32 v140, v228
	v_mov_b32_e32 v141, v229
	v_lshlrev_b32_e32 v131, 16, v138
	v_lshlrev_b32_e32 v143, 16, v139
	v_and_b32_e32 v145, 0xffff0000, v139
	v_lshlrev_b32_e32 v139, 16, v140
	v_mul_f32_e32 v131, 0xbfb8aa3b, v131
	v_and_b32_e32 v142, 0xffff0000, v138
	v_exp_f32_e32 v138, v131
	v_mul_f32_e32 v131, 0xbfb8aa3b, v139
	v_and_b32_e32 v144, 0xffff0000, v140
	v_exp_f32_e32 v140, v131
	v_mul_f32_e32 v131, 0xbfb8aa3b, v142
	v_exp_f32_e32 v139, v131
	v_lshlrev_b32_e32 v162, 16, v141
	v_and_b32_e32 v163, 0xffff0000, v141
	v_pk_add_f32 v[138:139], v[138:139], 1.0 op_sel_hi:[1,0]
	s_nop 0
	v_div_scale_f32 v131, s[30:31], v139, v139, 1.0
	v_rcp_f32_e32 v141, v131
	s_nop 0
	v_fma_f32 v142, -v131, v141, 1.0
	v_fmac_f32_e32 v141, v142, v141
	v_div_scale_f32 v142, vcc, 1.0, v139, 1.0
	v_mul_f32_e32 v164, v142, v141
	v_fma_f32 v165, -v131, v164, v142
	v_fmac_f32_e32 v164, v165, v141
	v_fma_f32 v131, -v131, v164, v142
	v_div_fmas_f32 v131, v131, v141, v164
	v_div_fixup_f32 v139, v131, v139, 1.0
	v_div_scale_f32 v131, s[30:31], v138, v138, 1.0
	v_rcp_f32_e32 v141, v131
	s_nop 0
	v_fma_f32 v142, -v131, v141, 1.0
	v_fmac_f32_e32 v141, v142, v141
	v_div_scale_f32 v142, vcc, 1.0, v138, 1.0
	v_mul_f32_e32 v164, v142, v141
	v_fma_f32 v165, -v131, v164, v142
	v_fmac_f32_e32 v164, v165, v141
	v_fma_f32 v131, -v131, v164, v142
	v_div_fmas_f32 v131, v131, v141, v164
	v_div_fixup_f32 v138, v131, v138, 1.0
	v_mul_f32_e32 v131, 0xbfb8aa3b, v144
	v_exp_f32_e32 v141, v131
	v_pk_mul_f32 v[138:139], v[62:63], v[138:139]
	v_pk_add_f32 v[140:141], v[140:141], 1.0 op_sel_hi:[1,0]
	s_nop 0
	v_div_scale_f32 v131, s[30:31], v141, v141, 1.0
	v_rcp_f32_e32 v142, v131
	v_cvt_pk_bf16_f32 v138, v138, v139
	v_fma_f32 v144, -v131, v142, 1.0
	v_fmac_f32_e32 v142, v144, v142
	v_div_scale_f32 v144, vcc, 1.0, v141, 1.0
	v_mul_f32_e32 v164, v144, v142
	v_fma_f32 v165, -v131, v164, v144
	v_fmac_f32_e32 v164, v165, v142
	v_fma_f32 v131, -v131, v164, v144
	v_div_fmas_f32 v131, v131, v142, v164
	v_div_fixup_f32 v141, v131, v141, 1.0
	v_div_scale_f32 v131, s[30:31], v140, v140, 1.0
	v_rcp_f32_e32 v142, v131
	s_nop 0
	v_fma_f32 v144, -v131, v142, 1.0
	v_fmac_f32_e32 v142, v144, v142
	v_div_scale_f32 v144, vcc, 1.0, v140, 1.0
	v_mul_f32_e32 v164, v144, v142
	v_fma_f32 v165, -v131, v164, v144
	v_fmac_f32_e32 v164, v165, v142
	v_fma_f32 v131, -v131, v164, v144
	v_div_fmas_f32 v131, v131, v142, v164
	v_div_fixup_f32 v140, v131, v140, 1.0
	v_mul_f32_e32 v131, 0xbfb8aa3b, v143
	v_exp_f32_e32 v142, v131
	v_mul_f32_e32 v131, 0xbfb8aa3b, v162
	v_exp_f32_e32 v144, v131
	v_mul_f32_e32 v131, 0xbfb8aa3b, v145
	v_exp_f32_e32 v143, v131
	v_pk_mul_f32 v[140:141], v[54:55], v[140:141]
	v_pk_add_f32 v[142:143], v[142:143], 1.0 op_sel_hi:[1,0]
	s_nop 0
	v_div_scale_f32 v131, s[30:31], v143, v143, 1.0
	v_rcp_f32_e32 v145, v131
	v_cvt_pk_bf16_f32 v140, v140, v141
	v_fma_f32 v162, -v131, v145, 1.0
	v_fmac_f32_e32 v145, v162, v145
	v_div_scale_f32 v162, vcc, 1.0, v143, 1.0
	v_mul_f32_e32 v164, v162, v145
	v_fma_f32 v165, -v131, v164, v162
	v_fmac_f32_e32 v164, v165, v145
	v_fma_f32 v131, -v131, v164, v162
	v_div_fmas_f32 v131, v131, v145, v164
	v_div_fixup_f32 v143, v131, v143, 1.0
	v_div_scale_f32 v131, s[30:31], v142, v142, 1.0
	v_rcp_f32_e32 v145, v131
	s_nop 0
	v_fma_f32 v162, -v131, v145, 1.0
	v_fmac_f32_e32 v145, v162, v145
	v_div_scale_f32 v162, vcc, 1.0, v142, 1.0
	v_mul_f32_e32 v164, v162, v145
	v_fma_f32 v165, -v131, v164, v162
	v_fmac_f32_e32 v164, v165, v145
	v_fma_f32 v131, -v131, v164, v162
	v_div_fmas_f32 v131, v131, v145, v164
	v_div_fixup_f32 v142, v131, v142, 1.0
	v_mul_f32_e32 v131, 0xbfb8aa3b, v163
	v_exp_f32_e32 v145, v131
	v_pk_mul_f32 v[142:143], v[64:65], v[142:143]
	v_pk_add_f32 v[144:145], v[144:145], 1.0 op_sel_hi:[1,0]
	s_nop 0
	v_div_scale_f32 v131, s[30:31], v145, v145, 1.0
	v_rcp_f32_e32 v162, v131
	v_cvt_pk_bf16_f32 v139, v142, v143
	v_fma_f32 v163, -v131, v162, 1.0
	v_fmac_f32_e32 v162, v163, v162
	v_div_scale_f32 v163, vcc, 1.0, v145, 1.0
	v_mul_f32_e32 v164, v163, v162
	v_fma_f32 v165, -v131, v164, v163
	v_fmac_f32_e32 v164, v165, v162
	v_fma_f32 v131, -v131, v164, v163
	v_div_fmas_f32 v131, v131, v162, v164
	v_div_fixup_f32 v145, v131, v145, 1.0
	v_div_scale_f32 v131, s[30:31], v144, v144, 1.0
	v_rcp_f32_e32 v162, v131
	s_nop 0
	v_fma_f32 v163, -v131, v162, 1.0
	v_fmac_f32_e32 v162, v163, v162
	v_div_scale_f32 v163, vcc, 1.0, v144, 1.0
	v_mul_f32_e32 v164, v163, v162
	v_fma_f32 v165, -v131, v164, v163
	v_fmac_f32_e32 v164, v165, v162
	v_fma_f32 v131, -v131, v164, v163
	v_div_fmas_f32 v131, v131, v162, v164
	v_div_fixup_f32 v144, v131, v144, 1.0
	v_pk_mul_f32 v[144:145], v[56:57], v[144:145]
	s_nop 0
	v_cvt_pk_bf16_f32 v141, v144, v145
	global_store_dwordx4 v[134:135], v[138:141], off
	s_waitcnt vmcnt(15)
; __device__ __forceinline__ unsigned pk2(float lo, float hi) { return pg8::cvt_pk_bf16(lo, hi); }
; __device__ __forceinline__ float sigmoidf_(float x) { return 1.f / (1.f + __expf(-x)); }
;     __device__ __forceinline__ void operator()(const f32x4 (&acc)[2][2][4][2], const pg8::Unit& u, int wr, int wc, int fr, int fq) const {
;     ...
;                     const u32x4 gw = *(const u32x4*)(P + (size_t)row * NINP + GATEOFF + (gi - 1) * 2048 + col); float gt[8]; unpack8(gw, gt);
;                     const f32x4 v0 = acc[ai][bj][m][0], v1 = acc[ai][bj][m][1];
;                     float o[8];
; #pragma unroll
;                     for (int j = 0; j < 4; ++j) { o[j] = sigmoidf_(gt[j]) * v0[j]; o[4 + j] = sigmoidf_(gt[4 + j]) * v1[j]; }
;                     u32x4 w; w.x = pk2(o[0], o[1]); w.y = pk2(o[2], o[3]); w.z = pk2(o[4], o[5]); w.w = pk2(o[6], o[7]);
;                     *(u32x4*)(br + (size_t)row * D + col) = w; } }
	s_nop 1
	v_mov_b32_e32 v136, v230
	v_mov_b32_e32 v137, v231
	v_mov_b32_e32 v138, v232
	v_mov_b32_e32 v139, v233
	v_lshlrev_b32_e32 v131, 16, v136
	v_lshlrev_b32_e32 v141, 16, v137
	v_and_b32_e32 v143, 0xffff0000, v137
	v_lshlrev_b32_e32 v137, 16, v138
	v_mul_f32_e32 v131, 0xbfb8aa3b, v131
	v_and_b32_e32 v140, 0xffff0000, v136
	v_exp_f32_e32 v136, v131
	v_mul_f32_e32 v131, 0xbfb8aa3b, v137
	v_and_b32_e32 v142, 0xffff0000, v138
	v_exp_f32_e32 v138, v131
	v_mul_f32_e32 v131, 0xbfb8aa3b, v140
	v_exp_f32_e32 v137, v131
	v_lshlrev_b32_e32 v144, 16, v139
	v_and_b32_e32 v145, 0xffff0000, v139
	v_pk_add_f32 v[136:137], v[136:137], 1.0 op_sel_hi:[1,0]
	s_nop 0
	v_div_scale_f32 v131, s[30:31], v137, v137, 1.0
	v_rcp_f32_e32 v139, v131
	s_nop 0
	v_fma_f32 v140, -v131, v139, 1.0
	v_fmac_f32_e32 v139, v140, v139
	v_div_scale_f32 v140, vcc, 1.0, v137, 1.0
	v_mul_f32_e32 v162, v140, v139
	v_fma_f32 v163, -v131, v162, v140
	v_fmac_f32_e32 v162, v163, v139
	v_fma_f32 v131, -v131, v162, v140
	v_div_fmas_f32 v131, v131, v139, v162
	v_div_fixup_f32 v137, v131, v137, 1.0
	v_div_scale_f32 v131, s[30:31], v136, v136, 1.0
	v_rcp_f32_e32 v139, v131
	s_nop 0
	v_fma_f32 v140, -v131, v139, 1.0
	v_fmac_f32_e32 v139, v140, v139
	v_div_scale_f32 v140, vcc, 1.0, v136, 1.0
	v_mul_f32_e32 v162, v140, v139
	v_fma_f32 v163, -v131, v162, v140
	v_fmac_f32_e32 v162, v163, v139
	v_fma_f32 v131, -v131, v162, v140
	v_div_fmas_f32 v131, v131, v139, v162
	v_div_fixup_f32 v136, v131, v136, 1.0
	v_mul_f32_e32 v131, 0xbfb8aa3b, v142
	v_exp_f32_e32 v139, v131
	v_pk_mul_f32 v[136:137], v[58:59], v[136:137]
	v_pk_add_f32 v[138:139], v[138:139], 1.0 op_sel_hi:[1,0]
	s_nop 0
	v_div_scale_f32 v131, s[30:31], v139, v139, 1.0
	v_rcp_f32_e32 v140, v131
	v_cvt_pk_bf16_f32 v136, v136, v137
	v_fma_f32 v142, -v131, v140, 1.0
	v_fmac_f32_e32 v140, v142, v140
	v_div_scale_f32 v142, vcc, 1.0, v139, 1.0
	v_mul_f32_e32 v162, v142, v140
	v_fma_f32 v163, -v131, v162, v142
	v_fmac_f32_e32 v162, v163, v140
	v_fma_f32 v131, -v131, v162, v142
	v_div_fmas_f32 v131, v131, v140, v162
	v_div_fixup_f32 v139, v131, v139, 1.0
	v_div_scale_f32 v131, s[30:31], v138, v138, 1.0
	v_rcp_f32_e32 v140, v131
	s_nop 0
	v_fma_f32 v142, -v131, v140, 1.0
	v_fmac_f32_e32 v140, v142, v140
	v_div_scale_f32 v142, vcc, 1.0, v138, 1.0
	v_mul_f32_e32 v162, v142, v140
	v_fma_f32 v163, -v131, v162, v142
	v_fmac_f32_e32 v162, v163, v140
	v_fma_f32 v131, -v131, v162, v142
	v_div_fmas_f32 v131, v131, v140, v162
	v_div_fixup_f32 v138, v131, v138, 1.0
	v_mul_f32_e32 v131, 0xbfb8aa3b, v141
	v_exp_f32_e32 v140, v131
	v_mul_f32_e32 v131, 0xbfb8aa3b, v144
	v_exp_f32_e32 v142, v131
	v_mul_f32_e32 v131, 0xbfb8aa3b, v143
	v_exp_f32_e32 v141, v131
	v_pk_mul_f32 v[138:139], v[50:51], v[138:139]
	v_pk_add_f32 v[140:141], v[140:141], 1.0 op_sel_hi:[1,0]
	s_nop 0
	v_div_scale_f32 v131, s[30:31], v141, v141, 1.0
	v_rcp_f32_e32 v143, v131
	v_cvt_pk_bf16_f32 v138, v138, v139
	v_fma_f32 v144, -v131, v143, 1.0
	v_fmac_f32_e32 v143, v144, v143
	v_div_scale_f32 v144, vcc, 1.0, v141, 1.0
	v_mul_f32_e32 v162, v144, v143
	v_fma_f32 v163, -v131, v162, v144
	v_fmac_f32_e32 v162, v163, v143
	v_fma_f32 v131, -v131, v162, v144
	v_div_fmas_f32 v131, v131, v143, v162
	v_div_fixup_f32 v141, v131, v141, 1.0
	v_div_scale_f32 v131, s[30:31], v140, v140, 1.0
	v_rcp_f32_e32 v143, v131
	s_nop 0
	v_fma_f32 v144, -v131, v143, 1.0
	v_fmac_f32_e32 v143, v144, v143
	v_div_scale_f32 v144, vcc, 1.0, v140, 1.0
	v_mul_f32_e32 v162, v144, v143
	v_fma_f32 v163, -v131, v162, v144
	v_fmac_f32_e32 v162, v163, v143
	v_fma_f32 v131, -v131, v162, v144
	v_div_fmas_f32 v131, v131, v143, v162
	v_div_fixup_f32 v140, v131, v140, 1.0
	v_mul_f32_e32 v131, 0xbfb8aa3b, v145
	v_exp_f32_e32 v143, v131
	v_pk_mul_f32 v[140:141], v[60:61], v[140:141]
	v_pk_add_f32 v[142:143], v[142:143], 1.0 op_sel_hi:[1,0]
	s_nop 0
	v_div_scale_f32 v131, s[30:31], v143, v143, 1.0
	v_rcp_f32_e32 v144, v131
	v_cvt_pk_bf16_f32 v137, v140, v141
	v_fma_f32 v145, -v131, v144, 1.0
	v_fmac_f32_e32 v144, v145, v144
	v_div_scale_f32 v145, vcc, 1.0, v143, 1.0
	v_mul_f32_e32 v162, v145, v144
	v_fma_f32 v163, -v131, v162, v145
	v_fmac_f32_e32 v162, v163, v144
	v_fma_f32 v131, -v131, v162, v145
	v_div_fmas_f32 v131, v131, v144, v162
	v_div_fixup_f32 v143, v131, v143, 1.0
	v_div_scale_f32 v131, s[30:31], v142, v142, 1.0
	v_rcp_f32_e32 v144, v131
	s_nop 0
	v_fma_f32 v145, -v131, v144, 1.0
	v_fmac_f32_e32 v144, v145, v144
	v_div_scale_f32 v145, vcc, 1.0, v142, 1.0
	v_mul_f32_e32 v162, v145, v144
	v_fma_f32 v163, -v131, v162, v145
	v_fmac_f32_e32 v162, v163, v144
	v_fma_f32 v131, -v131, v162, v145
	v_div_fmas_f32 v131, v131, v144, v162
	v_div_fixup_f32 v142, v131, v142, 1.0
	v_pk_mul_f32 v[142:143], v[52:53], v[142:143]
	s_nop 0
	v_cvt_pk_bf16_f32 v139, v142, v143
	global_store_dwordx4 v[134:135], v[136:139], off offset:256
	s_nop 1
	v_add_u32_e32 v136, 0x90, v130
	v_ashrrev_i32_e32 v137, 31, v136
	v_lshlrev_b64 v[134:135], 12, v[136:137]
	v_mad_i64_i32 v[136:137], s[30:31], v136, s79, v[132:133]
	v_lshl_add_u64 v[136:137], v[136:137], 0, s[28:29]
	v_lshl_add_u64 v[138:139], v[136:137], 0, v[0:1]
	v_lshl_add_u64 v[136:137], v[138:139], 0, s[60:61]
	v_add_co_u32_e32 v138, vcc, s17, v138
	v_lshl_add_u64 v[134:135], s[26:27], 0, v[134:135]
	s_nop 0
	v_addc_co_u32_e32 v139, vcc, 0, v139, vcc
	v_lshl_add_u64 v[134:135], v[134:135], 0, v[0:1]
	s_waitcnt vmcnt(15)
; __device__ __forceinline__ unsigned pk2(float lo, float hi) { return pg8::cvt_pk_bf16(lo, hi); }
; __device__ __forceinline__ float sigmoidf_(float x) { return 1.f / (1.f + __expf(-x)); }
;     __device__ __forceinline__ void operator()(const f32x4 (&acc)[2][2][4][2], const pg8::Unit& u, int wr, int wc, int fr, int fq) const {
;     ...
;                     const u32x4 gw = *(const u32x4*)(P + (size_t)row * NINP + GATEOFF + (gi - 1) * 2048 + col); float gt[8]; unpack8(gw, gt);
;                     const f32x4 v0 = acc[ai][bj][m][0], v1 = acc[ai][bj][m][1];
;                     float o[8];
; #pragma unroll
;                     for (int j = 0; j < 4; ++j) { o[j] = sigmoidf_(gt[j]) * v0[j]; o[4 + j] = sigmoidf_(gt[4 + j]) * v1[j]; }
;                     u32x4 w; w.x = pk2(o[0], o[1]); w.y = pk2(o[2], o[3]); w.z = pk2(o[4], o[5]); w.w = pk2(o[6], o[7]);
;                     *(u32x4*)(br + (size_t)row * D + col) = w; } }
	s_nop 1
	v_mov_b32_e32 v138, v234
	v_mov_b32_e32 v139, v235
	v_mov_b32_e32 v140, v236
	v_mov_b32_e32 v141, v237
	v_lshlrev_b32_e32 v131, 16, v138
	v_lshlrev_b32_e32 v143, 16, v139
	v_and_b32_e32 v145, 0xffff0000, v139
	v_lshlrev_b32_e32 v139, 16, v140
	v_mul_f32_e32 v131, 0xbfb8aa3b, v131
	v_and_b32_e32 v142, 0xffff0000, v138
	v_exp_f32_e32 v138, v131
	v_mul_f32_e32 v131, 0xbfb8aa3b, v139
	v_and_b32_e32 v144, 0xffff0000, v140
	v_exp_f32_e32 v140, v131
	v_mul_f32_e32 v131, 0xbfb8aa3b, v142
	v_exp_f32_e32 v139, v131
	v_lshlrev_b32_e32 v162, 16, v141
	v_and_b32_e32 v163, 0xffff0000, v141
	v_pk_add_f32 v[138:139], v[138:139], 1.0 op_sel_hi:[1,0]
	s_nop 0
	v_div_scale_f32 v131, s[30:31], v139, v139, 1.0
	v_rcp_f32_e32 v141, v131
	s_nop 0
	v_fma_f32 v142, -v131, v141, 1.0
	v_fmac_f32_e32 v141, v142, v141
	v_div_scale_f32 v142, vcc, 1.0, v139, 1.0
	v_mul_f32_e32 v164, v142, v141
	v_fma_f32 v165, -v131, v164, v142
	v_fmac_f32_e32 v164, v165, v141
	v_fma_f32 v131, -v131, v164, v142
	v_div_fmas_f32 v131, v131, v141, v164
	v_div_fixup_f32 v139, v131, v139, 1.0
	v_div_scale_f32 v131, s[30:31], v138, v138, 1.0
	v_rcp_f32_e32 v141, v131
	s_nop 0
	v_fma_f32 v142, -v131, v141, 1.0
	v_fmac_f32_e32 v141, v142, v141
	v_div_scale_f32 v142, vcc, 1.0, v138, 1.0
	v_mul_f32_e32 v164, v142, v141
	v_fma_f32 v165, -v131, v164, v142
	v_fmac_f32_e32 v164, v165, v141
	v_fma_f32 v131, -v131, v164, v142
	v_div_fmas_f32 v131, v131, v141, v164
	v_div_fixup_f32 v138, v131, v138, 1.0
	v_mul_f32_e32 v131, 0xbfb8aa3b, v144
	v_exp_f32_e32 v141, v131
	v_pk_mul_f32 v[138:139], v[46:47], v[138:139]
	v_pk_add_f32 v[140:141], v[140:141], 1.0 op_sel_hi:[1,0]
	s_nop 0
	v_div_scale_f32 v131, s[30:31], v141, v141, 1.0
	v_rcp_f32_e32 v142, v131
	v_cvt_pk_bf16_f32 v138, v138, v139
	v_fma_f32 v144, -v131, v142, 1.0
	v_fmac_f32_e32 v142, v144, v142
	v_div_scale_f32 v144, vcc, 1.0, v141, 1.0
	v_mul_f32_e32 v164, v144, v142
	v_fma_f32 v165, -v131, v164, v144
	v_fmac_f32_e32 v164, v165, v142
	v_fma_f32 v131, -v131, v164, v144
	v_div_fmas_f32 v131, v131, v142, v164
	v_div_fixup_f32 v141, v131, v141, 1.0
	v_div_scale_f32 v131, s[30:31], v140, v140, 1.0
	v_rcp_f32_e32 v142, v131
	s_nop 0
	v_fma_f32 v144, -v131, v142, 1.0
	v_fmac_f32_e32 v142, v144, v142
	v_div_scale_f32 v144, vcc, 1.0, v140, 1.0
	v_mul_f32_e32 v164, v144, v142
	v_fma_f32 v165, -v131, v164, v144
	v_fmac_f32_e32 v164, v165, v142
	v_fma_f32 v131, -v131, v164, v144
	v_div_fmas_f32 v131, v131, v142, v164
	v_div_fixup_f32 v140, v131, v140, 1.0
	v_mul_f32_e32 v131, 0xbfb8aa3b, v143
	v_exp_f32_e32 v142, v131
	v_mul_f32_e32 v131, 0xbfb8aa3b, v162
	v_exp_f32_e32 v144, v131
	v_mul_f32_e32 v131, 0xbfb8aa3b, v145
	v_exp_f32_e32 v143, v131
	v_pk_mul_f32 v[140:141], v[38:39], v[140:141]
	v_pk_add_f32 v[142:143], v[142:143], 1.0 op_sel_hi:[1,0]
	s_nop 0
	v_div_scale_f32 v131, s[30:31], v143, v143, 1.0
	v_rcp_f32_e32 v145, v131
	v_cvt_pk_bf16_f32 v140, v140, v141
	v_fma_f32 v162, -v131, v145, 1.0
	v_fmac_f32_e32 v145, v162, v145
	v_div_scale_f32 v162, vcc, 1.0, v143, 1.0
	v_mul_f32_e32 v164, v162, v145
	v_fma_f32 v165, -v131, v164, v162
	v_fmac_f32_e32 v164, v165, v145
	v_fma_f32 v131, -v131, v164, v162
	v_div_fmas_f32 v131, v131, v145, v164
	v_div_fixup_f32 v143, v131, v143, 1.0
	v_div_scale_f32 v131, s[30:31], v142, v142, 1.0
	v_rcp_f32_e32 v145, v131
	s_nop 0
	v_fma_f32 v162, -v131, v145, 1.0
	v_fmac_f32_e32 v145, v162, v145
	v_div_scale_f32 v162, vcc, 1.0, v142, 1.0
	v_mul_f32_e32 v164, v162, v145
	v_fma_f32 v165, -v131, v164, v162
	v_fmac_f32_e32 v164, v165, v145
	v_fma_f32 v131, -v131, v164, v162
	v_div_fmas_f32 v131, v131, v145, v164
	v_div_fixup_f32 v142, v131, v142, 1.0
	v_mul_f32_e32 v131, 0xbfb8aa3b, v163
	v_exp_f32_e32 v145, v131
	v_pk_mul_f32 v[142:143], v[48:49], v[142:143]
	v_pk_add_f32 v[144:145], v[144:145], 1.0 op_sel_hi:[1,0]
	s_nop 0
	v_div_scale_f32 v131, s[30:31], v145, v145, 1.0
	v_rcp_f32_e32 v162, v131
	v_cvt_pk_bf16_f32 v139, v142, v143
	v_fma_f32 v163, -v131, v162, 1.0
	v_fmac_f32_e32 v162, v163, v162
	v_div_scale_f32 v163, vcc, 1.0, v145, 1.0
	v_mul_f32_e32 v164, v163, v162
	v_fma_f32 v165, -v131, v164, v163
	v_fmac_f32_e32 v164, v165, v162
	v_fma_f32 v131, -v131, v164, v163
	v_div_fmas_f32 v131, v131, v162, v164
	v_div_fixup_f32 v145, v131, v145, 1.0
	v_div_scale_f32 v131, s[30:31], v144, v144, 1.0
	v_rcp_f32_e32 v162, v131
	s_nop 0
	v_fma_f32 v163, -v131, v162, 1.0
	v_fmac_f32_e32 v162, v163, v162
	v_div_scale_f32 v163, vcc, 1.0, v144, 1.0
	v_mul_f32_e32 v164, v163, v162
	v_fma_f32 v165, -v131, v164, v163
	v_fmac_f32_e32 v164, v165, v162
	v_fma_f32 v131, -v131, v164, v163
	v_div_fmas_f32 v131, v131, v162, v164
	v_div_fixup_f32 v144, v131, v144, 1.0
	v_pk_mul_f32 v[144:145], v[40:41], v[144:145]
	s_nop 0
	v_cvt_pk_bf16_f32 v141, v144, v145
	global_store_dwordx4 v[134:135], v[138:141], off
	s_waitcnt vmcnt(15)
; __device__ __forceinline__ unsigned pk2(float lo, float hi) { return pg8::cvt_pk_bf16(lo, hi); }
; __device__ __forceinline__ float sigmoidf_(float x) { return 1.f / (1.f + __expf(-x)); }
;     __device__ __forceinline__ void operator()(const f32x4 (&acc)[2][2][4][2], const pg8::Unit& u, int wr, int wc, int fr, int fq) const {
;     ...
;                     const u32x4 gw = *(const u32x4*)(P + (size_t)row * NINP + GATEOFF + (gi - 1) * 2048 + col); float gt[8]; unpack8(gw, gt);
;                     const f32x4 v0 = acc[ai][bj][m][0], v1 = acc[ai][bj][m][1];
;                     float o[8];
; #pragma unroll
;                     for (int j = 0; j < 4; ++j) { o[j] = sigmoidf_(gt[j]) * v0[j]; o[4 + j] = sigmoidf_(gt[4 + j]) * v1[j]; }
;                     u32x4 w; w.x = pk2(o[0], o[1]); w.y = pk2(o[2], o[3]); w.z = pk2(o[4], o[5]); w.w = pk2(o[6], o[7]);
;                     *(u32x4*)(br + (size_t)row * D + col) = w; } }
	s_nop 1
	v_mov_b32_e32 v136, v238
	v_mov_b32_e32 v137, v239
	v_mov_b32_e32 v138, v240
	v_mov_b32_e32 v139, v241
	v_lshlrev_b32_e32 v131, 16, v136
	v_lshlrev_b32_e32 v141, 16, v137
	v_and_b32_e32 v143, 0xffff0000, v137
	v_lshlrev_b32_e32 v137, 16, v138
	v_mul_f32_e32 v131, 0xbfb8aa3b, v131
	v_and_b32_e32 v140, 0xffff0000, v136
	v_exp_f32_e32 v136, v131
	v_mul_f32_e32 v131, 0xbfb8aa3b, v137
	v_and_b32_e32 v142, 0xffff0000, v138
	v_exp_f32_e32 v138, v131
	v_mul_f32_e32 v131, 0xbfb8aa3b, v140
	v_exp_f32_e32 v137, v131
	v_lshlrev_b32_e32 v144, 16, v139
	v_and_b32_e32 v145, 0xffff0000, v139
	v_pk_add_f32 v[136:137], v[136:137], 1.0 op_sel_hi:[1,0]
	s_nop 0
	v_div_scale_f32 v131, s[30:31], v137, v137, 1.0
	v_rcp_f32_e32 v139, v131
	s_nop 0
	v_fma_f32 v140, -v131, v139, 1.0
	v_fmac_f32_e32 v139, v140, v139
	v_div_scale_f32 v140, vcc, 1.0, v137, 1.0
	v_mul_f32_e32 v162, v140, v139
	v_fma_f32 v163, -v131, v162, v140
	v_fmac_f32_e32 v162, v163, v139
	v_fma_f32 v131, -v131, v162, v140
	v_div_fmas_f32 v131, v131, v139, v162
	v_div_fixup_f32 v137, v131, v137, 1.0
	v_div_scale_f32 v131, s[30:31], v136, v136, 1.0
	v_rcp_f32_e32 v139, v131
	s_nop 0
	v_fma_f32 v140, -v131, v139, 1.0
	v_fmac_f32_e32 v139, v140, v139
	v_div_scale_f32 v140, vcc, 1.0, v136, 1.0
	v_mul_f32_e32 v162, v140, v139
	v_fma_f32 v163, -v131, v162, v140
	v_fmac_f32_e32 v162, v163, v139
	v_fma_f32 v131, -v131, v162, v140
	v_div_fmas_f32 v131, v131, v139, v162
	v_div_fixup_f32 v136, v131, v136, 1.0
	v_mul_f32_e32 v131, 0xbfb8aa3b, v142
	v_exp_f32_e32 v139, v131
	v_pk_mul_f32 v[136:137], v[42:43], v[136:137]
	v_pk_add_f32 v[138:139], v[138:139], 1.0 op_sel_hi:[1,0]
	s_nop 0
	v_div_scale_f32 v131, s[30:31], v139, v139, 1.0
	v_rcp_f32_e32 v140, v131
	v_cvt_pk_bf16_f32 v136, v136, v137
	v_fma_f32 v142, -v131, v140, 1.0
	v_fmac_f32_e32 v140, v142, v140
	v_div_scale_f32 v142, vcc, 1.0, v139, 1.0
	v_mul_f32_e32 v162, v142, v140
	v_fma_f32 v163, -v131, v162, v142
	v_fmac_f32_e32 v162, v163, v140
	v_fma_f32 v131, -v131, v162, v142
	v_div_fmas_f32 v131, v131, v140, v162
	v_div_fixup_f32 v139, v131, v139, 1.0
	v_div_scale_f32 v131, s[30:31], v138, v138, 1.0
	v_rcp_f32_e32 v140, v131
	s_nop 0
	v_fma_f32 v142, -v131, v140, 1.0
	v_fmac_f32_e32 v140, v142, v140
	v_div_scale_f32 v142, vcc, 1.0, v138, 1.0
	v_mul_f32_e32 v162, v142, v140
	v_fma_f32 v163, -v131, v162, v142
	v_fmac_f32_e32 v162, v163, v140
	v_fma_f32 v131, -v131, v162, v142
	v_div_fmas_f32 v131, v131, v140, v162
	v_div_fixup_f32 v138, v131, v138, 1.0
	v_mul_f32_e32 v131, 0xbfb8aa3b, v141
	v_exp_f32_e32 v140, v131
	v_mul_f32_e32 v131, 0xbfb8aa3b, v144
	v_exp_f32_e32 v142, v131
	v_mul_f32_e32 v131, 0xbfb8aa3b, v143
	v_exp_f32_e32 v141, v131
	v_pk_mul_f32 v[138:139], v[34:35], v[138:139]
	v_pk_add_f32 v[140:141], v[140:141], 1.0 op_sel_hi:[1,0]
	s_nop 0
	v_div_scale_f32 v131, s[30:31], v141, v141, 1.0
	v_rcp_f32_e32 v143, v131
	v_cvt_pk_bf16_f32 v138, v138, v139
	v_fma_f32 v144, -v131, v143, 1.0
	v_fmac_f32_e32 v143, v144, v143
	v_div_scale_f32 v144, vcc, 1.0, v141, 1.0
	v_mul_f32_e32 v162, v144, v143
	v_fma_f32 v163, -v131, v162, v144
	v_fmac_f32_e32 v162, v163, v143
	v_fma_f32 v131, -v131, v162, v144
	v_div_fmas_f32 v131, v131, v143, v162
	v_div_fixup_f32 v141, v131, v141, 1.0
	v_div_scale_f32 v131, s[30:31], v140, v140, 1.0
	v_rcp_f32_e32 v143, v131
	s_nop 0
	v_fma_f32 v144, -v131, v143, 1.0
	v_fmac_f32_e32 v143, v144, v143
	v_div_scale_f32 v144, vcc, 1.0, v140, 1.0
	v_mul_f32_e32 v162, v144, v143
	v_fma_f32 v163, -v131, v162, v144
	v_fmac_f32_e32 v162, v163, v143
	v_fma_f32 v131, -v131, v162, v144
	v_div_fmas_f32 v131, v131, v143, v162
	v_div_fixup_f32 v140, v131, v140, 1.0
	v_mul_f32_e32 v131, 0xbfb8aa3b, v145
	v_exp_f32_e32 v143, v131
	v_pk_mul_f32 v[140:141], v[44:45], v[140:141]
	v_pk_add_f32 v[142:143], v[142:143], 1.0 op_sel_hi:[1,0]
	s_nop 0
	v_div_scale_f32 v131, s[30:31], v143, v143, 1.0
	v_rcp_f32_e32 v144, v131
	v_cvt_pk_bf16_f32 v137, v140, v141
	v_fma_f32 v145, -v131, v144, 1.0
	v_fmac_f32_e32 v144, v145, v144
	v_div_scale_f32 v145, vcc, 1.0, v143, 1.0
	v_mul_f32_e32 v162, v145, v144
	v_fma_f32 v163, -v131, v162, v145
	v_fmac_f32_e32 v162, v163, v144
	v_fma_f32 v131, -v131, v162, v145
	v_div_fmas_f32 v131, v131, v144, v162
	v_div_fixup_f32 v143, v131, v143, 1.0
	v_div_scale_f32 v131, s[30:31], v142, v142, 1.0
	v_rcp_f32_e32 v144, v131
	s_nop 0
	v_fma_f32 v145, -v131, v144, 1.0
	v_fmac_f32_e32 v144, v145, v144
	v_div_scale_f32 v145, vcc, 1.0, v142, 1.0
	v_mul_f32_e32 v162, v145, v144
	v_fma_f32 v163, -v131, v162, v145
	v_fmac_f32_e32 v162, v163, v144
	v_fma_f32 v131, -v131, v162, v145
	v_div_fmas_f32 v131, v131, v144, v162
	v_div_fixup_f32 v142, v131, v142, 1.0
	v_pk_mul_f32 v[142:143], v[36:37], v[142:143]
	s_nop 0
	v_cvt_pk_bf16_f32 v139, v142, v143
	global_store_dwordx4 v[134:135], v[136:139], off offset:256
	s_nop 1
	v_add_u32_e32 v136, 0xa0, v130
	v_ashrrev_i32_e32 v137, 31, v136
	v_lshlrev_b64 v[134:135], 12, v[136:137]
	v_mad_i64_i32 v[136:137], s[30:31], v136, s79, v[132:133]
	v_lshl_add_u64 v[136:137], v[136:137], 0, s[28:29]
	v_lshl_add_u64 v[138:139], v[136:137], 0, v[0:1]
	v_lshl_add_u64 v[136:137], v[138:139], 0, s[60:61]
	v_add_co_u32_e32 v138, vcc, s17, v138
	v_lshl_add_u64 v[134:135], s[26:27], 0, v[134:135]
	s_nop 0
	v_addc_co_u32_e32 v139, vcc, 0, v139, vcc
	v_lshl_add_u64 v[134:135], v[134:135], 0, v[0:1]
	s_waitcnt vmcnt(15)
; __device__ __forceinline__ unsigned pk2(float lo, float hi) { return pg8::cvt_pk_bf16(lo, hi); }
; __device__ __forceinline__ float sigmoidf_(float x) { return 1.f / (1.f + __expf(-x)); }
;     __device__ __forceinline__ void operator()(const f32x4 (&acc)[2][2][4][2], const pg8::Unit& u, int wr, int wc, int fr, int fq) const {
;     ...
;                     const u32x4 gw = *(const u32x4*)(P + (size_t)row * NINP + GATEOFF + (gi - 1) * 2048 + col); float gt[8]; unpack8(gw, gt);
;                     const f32x4 v0 = acc[ai][bj][m][0], v1 = acc[ai][bj][m][1];
;                     float o[8];
; #pragma unroll
;                     for (int j = 0; j < 4; ++j) { o[j] = sigmoidf_(gt[j]) * v0[j]; o[4 + j] = sigmoidf_(gt[4 + j]) * v1[j]; }
;                     u32x4 w; w.x = pk2(o[0], o[1]); w.y = pk2(o[2], o[3]); w.z = pk2(o[4], o[5]); w.w = pk2(o[6], o[7]);
;                     *(u32x4*)(br + (size_t)row * D + col) = w; } }
	s_nop 1
	v_mov_b32_e32 v138, v242
	v_mov_b32_e32 v139, v243
	v_mov_b32_e32 v140, v244
	v_mov_b32_e32 v141, v245
	v_lshlrev_b32_e32 v131, 16, v138
	v_lshlrev_b32_e32 v143, 16, v139
	v_and_b32_e32 v145, 0xffff0000, v139
	v_lshlrev_b32_e32 v139, 16, v140
	v_mul_f32_e32 v131, 0xbfb8aa3b, v131
	v_and_b32_e32 v142, 0xffff0000, v138
	v_exp_f32_e32 v138, v131
	v_mul_f32_e32 v131, 0xbfb8aa3b, v139
	v_and_b32_e32 v144, 0xffff0000, v140
	v_exp_f32_e32 v140, v131
	v_mul_f32_e32 v131, 0xbfb8aa3b, v142
	v_exp_f32_e32 v139, v131
	v_lshlrev_b32_e32 v162, 16, v141
	v_and_b32_e32 v163, 0xffff0000, v141
	v_pk_add_f32 v[138:139], v[138:139], 1.0 op_sel_hi:[1,0]
	s_nop 0
	v_div_scale_f32 v131, s[30:31], v139, v139, 1.0
	v_rcp_f32_e32 v141, v131
	s_nop 0
	v_fma_f32 v142, -v131, v141, 1.0
	v_fmac_f32_e32 v141, v142, v141
	v_div_scale_f32 v142, vcc, 1.0, v139, 1.0
	v_mul_f32_e32 v164, v142, v141
	v_fma_f32 v165, -v131, v164, v142
	v_fmac_f32_e32 v164, v165, v141
	v_fma_f32 v131, -v131, v164, v142
	v_div_fmas_f32 v131, v131, v141, v164
	v_div_fixup_f32 v139, v131, v139, 1.0
	v_div_scale_f32 v131, s[30:31], v138, v138, 1.0
	v_rcp_f32_e32 v141, v131
	s_nop 0
	v_fma_f32 v142, -v131, v141, 1.0
	v_fmac_f32_e32 v141, v142, v141
	v_div_scale_f32 v142, vcc, 1.0, v138, 1.0
	v_mul_f32_e32 v164, v142, v141
	v_fma_f32 v165, -v131, v164, v142
	v_fmac_f32_e32 v164, v165, v141
	v_fma_f32 v131, -v131, v164, v142
	v_div_fmas_f32 v131, v131, v141, v164
	v_div_fixup_f32 v138, v131, v138, 1.0
	v_mul_f32_e32 v131, 0xbfb8aa3b, v144
	v_exp_f32_e32 v141, v131
	v_pk_mul_f32 v[138:139], v[30:31], v[138:139]
	v_pk_add_f32 v[140:141], v[140:141], 1.0 op_sel_hi:[1,0]
	s_nop 0
	v_div_scale_f32 v131, s[30:31], v141, v141, 1.0
	v_rcp_f32_e32 v142, v131
	v_cvt_pk_bf16_f32 v138, v138, v139
	v_fma_f32 v144, -v131, v142, 1.0
	v_fmac_f32_e32 v142, v144, v142
	v_div_scale_f32 v144, vcc, 1.0, v141, 1.0
	v_mul_f32_e32 v164, v144, v142
	v_fma_f32 v165, -v131, v164, v144
	v_fmac_f32_e32 v164, v165, v142
	v_fma_f32 v131, -v131, v164, v144
	v_div_fmas_f32 v131, v131, v142, v164
	v_div_fixup_f32 v141, v131, v141, 1.0
	v_div_scale_f32 v131, s[30:31], v140, v140, 1.0
	v_rcp_f32_e32 v142, v131
	s_nop 0
	v_fma_f32 v144, -v131, v142, 1.0
	v_fmac_f32_e32 v142, v144, v142
	v_div_scale_f32 v144, vcc, 1.0, v140, 1.0
	v_mul_f32_e32 v164, v144, v142
	v_fma_f32 v165, -v131, v164, v144
	v_fmac_f32_e32 v164, v165, v142
	v_fma_f32 v131, -v131, v164, v144
	v_div_fmas_f32 v131, v131, v142, v164
	v_div_fixup_f32 v140, v131, v140, 1.0
	v_mul_f32_e32 v131, 0xbfb8aa3b, v143
	v_exp_f32_e32 v142, v131
	v_mul_f32_e32 v131, 0xbfb8aa3b, v162
	v_exp_f32_e32 v144, v131
	v_mul_f32_e32 v131, 0xbfb8aa3b, v145
	v_exp_f32_e32 v143, v131
	v_pk_mul_f32 v[140:141], v[22:23], v[140:141]
	v_pk_add_f32 v[142:143], v[142:143], 1.0 op_sel_hi:[1,0]
	s_nop 0
	v_div_scale_f32 v131, s[30:31], v143, v143, 1.0
	v_rcp_f32_e32 v145, v131
	v_cvt_pk_bf16_f32 v140, v140, v141
	v_fma_f32 v162, -v131, v145, 1.0
	v_fmac_f32_e32 v145, v162, v145
	v_div_scale_f32 v162, vcc, 1.0, v143, 1.0
	v_mul_f32_e32 v164, v162, v145
	v_fma_f32 v165, -v131, v164, v162
	v_fmac_f32_e32 v164, v165, v145
	v_fma_f32 v131, -v131, v164, v162
	v_div_fmas_f32 v131, v131, v145, v164
	v_div_fixup_f32 v143, v131, v143, 1.0
	v_div_scale_f32 v131, s[30:31], v142, v142, 1.0
	v_rcp_f32_e32 v145, v131
	s_nop 0
	v_fma_f32 v162, -v131, v145, 1.0
	v_fmac_f32_e32 v145, v162, v145
	v_div_scale_f32 v162, vcc, 1.0, v142, 1.0
	v_mul_f32_e32 v164, v162, v145
	v_fma_f32 v165, -v131, v164, v162
	v_fmac_f32_e32 v164, v165, v145
	v_fma_f32 v131, -v131, v164, v162
	v_div_fmas_f32 v131, v131, v145, v164
	v_div_fixup_f32 v142, v131, v142, 1.0
	v_mul_f32_e32 v131, 0xbfb8aa3b, v163
	v_exp_f32_e32 v145, v131
	v_pk_mul_f32 v[142:143], v[32:33], v[142:143]
	v_pk_add_f32 v[144:145], v[144:145], 1.0 op_sel_hi:[1,0]
	s_nop 0
	v_div_scale_f32 v131, s[30:31], v145, v145, 1.0
	v_rcp_f32_e32 v162, v131
	v_cvt_pk_bf16_f32 v139, v142, v143
	v_fma_f32 v163, -v131, v162, 1.0
	v_fmac_f32_e32 v162, v163, v162
	v_div_scale_f32 v163, vcc, 1.0, v145, 1.0
	v_mul_f32_e32 v164, v163, v162
	v_fma_f32 v165, -v131, v164, v163
	v_fmac_f32_e32 v164, v165, v162
	v_fma_f32 v131, -v131, v164, v163
	v_div_fmas_f32 v131, v131, v162, v164
	v_div_fixup_f32 v145, v131, v145, 1.0
	v_div_scale_f32 v131, s[30:31], v144, v144, 1.0
	v_rcp_f32_e32 v162, v131
	s_nop 0
	v_fma_f32 v163, -v131, v162, 1.0
	v_fmac_f32_e32 v162, v163, v162
	v_div_scale_f32 v163, vcc, 1.0, v144, 1.0
	v_mul_f32_e32 v164, v163, v162
	v_fma_f32 v165, -v131, v164, v163
	v_fmac_f32_e32 v164, v165, v162
	v_fma_f32 v131, -v131, v164, v163
	v_div_fmas_f32 v131, v131, v162, v164
	v_div_fixup_f32 v144, v131, v144, 1.0
	v_pk_mul_f32 v[144:145], v[24:25], v[144:145]
	s_nop 0
	v_cvt_pk_bf16_f32 v141, v144, v145
	global_store_dwordx4 v[134:135], v[138:141], off
	s_waitcnt vmcnt(15)
; __device__ __forceinline__ unsigned pk2(float lo, float hi) { return pg8::cvt_pk_bf16(lo, hi); }
; __device__ __forceinline__ float sigmoidf_(float x) { return 1.f / (1.f + __expf(-x)); }
;     __device__ __forceinline__ void operator()(const f32x4 (&acc)[2][2][4][2], const pg8::Unit& u, int wr, int wc, int fr, int fq) const {
;     ...
;                     const u32x4 gw = *(const u32x4*)(P + (size_t)row * NINP + GATEOFF + (gi - 1) * 2048 + col); float gt[8]; unpack8(gw, gt);
;                     const f32x4 v0 = acc[ai][bj][m][0], v1 = acc[ai][bj][m][1];
;                     float o[8];
; #pragma unroll
;                     for (int j = 0; j < 4; ++j) { o[j] = sigmoidf_(gt[j]) * v0[j]; o[4 + j] = sigmoidf_(gt[4 + j]) * v1[j]; }
;                     u32x4 w; w.x = pk2(o[0], o[1]); w.y = pk2(o[2], o[3]); w.z = pk2(o[4], o[5]); w.w = pk2(o[6], o[7]);
;                     *(u32x4*)(br + (size_t)row * D + col) = w; } }
	s_nop 1
	v_mov_b32_e32 v136, v246
	v_mov_b32_e32 v137, v247
	v_mov_b32_e32 v138, v248
	v_mov_b32_e32 v139, v249
	v_lshlrev_b32_e32 v131, 16, v136
	v_lshlrev_b32_e32 v141, 16, v137
	v_and_b32_e32 v143, 0xffff0000, v137
	v_lshlrev_b32_e32 v137, 16, v138
	v_mul_f32_e32 v131, 0xbfb8aa3b, v131
	v_and_b32_e32 v140, 0xffff0000, v136
	v_exp_f32_e32 v136, v131
	v_mul_f32_e32 v131, 0xbfb8aa3b, v137
	v_and_b32_e32 v142, 0xffff0000, v138
	v_exp_f32_e32 v138, v131
	v_mul_f32_e32 v131, 0xbfb8aa3b, v140
	v_exp_f32_e32 v137, v131
	v_lshlrev_b32_e32 v144, 16, v139
	v_and_b32_e32 v145, 0xffff0000, v139
	v_pk_add_f32 v[136:137], v[136:137], 1.0 op_sel_hi:[1,0]
	s_nop 0
	v_div_scale_f32 v131, s[30:31], v137, v137, 1.0
	v_rcp_f32_e32 v139, v131
	s_nop 0
	v_fma_f32 v140, -v131, v139, 1.0
	v_fmac_f32_e32 v139, v140, v139
	v_div_scale_f32 v140, vcc, 1.0, v137, 1.0
	v_mul_f32_e32 v162, v140, v139
	v_fma_f32 v163, -v131, v162, v140
	v_fmac_f32_e32 v162, v163, v139
	v_fma_f32 v131, -v131, v162, v140
	v_div_fmas_f32 v131, v131, v139, v162
	v_div_fixup_f32 v137, v131, v137, 1.0
	v_div_scale_f32 v131, s[30:31], v136, v136, 1.0
	v_rcp_f32_e32 v139, v131
	s_nop 0
	v_fma_f32 v140, -v131, v139, 1.0
	v_fmac_f32_e32 v139, v140, v139
	v_div_scale_f32 v140, vcc, 1.0, v136, 1.0
	v_mul_f32_e32 v162, v140, v139
	v_fma_f32 v163, -v131, v162, v140
	v_fmac_f32_e32 v162, v163, v139
	v_fma_f32 v131, -v131, v162, v140
	v_div_fmas_f32 v131, v131, v139, v162
	v_div_fixup_f32 v136, v131, v136, 1.0
	v_mul_f32_e32 v131, 0xbfb8aa3b, v142
	v_exp_f32_e32 v139, v131
	v_pk_mul_f32 v[136:137], v[26:27], v[136:137]
	v_pk_add_f32 v[138:139], v[138:139], 1.0 op_sel_hi:[1,0]
	s_nop 0
	v_div_scale_f32 v131, s[30:31], v139, v139, 1.0
	v_rcp_f32_e32 v140, v131
	v_cvt_pk_bf16_f32 v136, v136, v137
	v_fma_f32 v142, -v131, v140, 1.0
	v_fmac_f32_e32 v140, v142, v140
	v_div_scale_f32 v142, vcc, 1.0, v139, 1.0
	v_mul_f32_e32 v162, v142, v140
	v_fma_f32 v163, -v131, v162, v142
	v_fmac_f32_e32 v162, v163, v140
	v_fma_f32 v131, -v131, v162, v142
	v_div_fmas_f32 v131, v131, v140, v162
	v_div_fixup_f32 v139, v131, v139, 1.0
	v_div_scale_f32 v131, s[30:31], v138, v138, 1.0
	v_rcp_f32_e32 v140, v131
	s_nop 0
	v_fma_f32 v142, -v131, v140, 1.0
	v_fmac_f32_e32 v140, v142, v140
	v_div_scale_f32 v142, vcc, 1.0, v138, 1.0
	v_mul_f32_e32 v162, v142, v140
	v_fma_f32 v163, -v131, v162, v142
	v_fmac_f32_e32 v162, v163, v140
	v_fma_f32 v131, -v131, v162, v142
	v_div_fmas_f32 v131, v131, v140, v162
	v_div_fixup_f32 v138, v131, v138, 1.0
	v_mul_f32_e32 v131, 0xbfb8aa3b, v141
	v_exp_f32_e32 v140, v131
	v_mul_f32_e32 v131, 0xbfb8aa3b, v144
	v_exp_f32_e32 v142, v131
	v_mul_f32_e32 v131, 0xbfb8aa3b, v143
	v_exp_f32_e32 v141, v131
	v_pk_mul_f32 v[138:139], v[18:19], v[138:139]
	v_pk_add_f32 v[140:141], v[140:141], 1.0 op_sel_hi:[1,0]
	s_nop 0
	v_div_scale_f32 v131, s[30:31], v141, v141, 1.0
	v_rcp_f32_e32 v143, v131
	v_cvt_pk_bf16_f32 v138, v138, v139
	v_fma_f32 v144, -v131, v143, 1.0
	v_fmac_f32_e32 v143, v144, v143
	v_div_scale_f32 v144, vcc, 1.0, v141, 1.0
	v_mul_f32_e32 v162, v144, v143
	v_fma_f32 v163, -v131, v162, v144
	v_fmac_f32_e32 v162, v163, v143
	v_fma_f32 v131, -v131, v162, v144
	v_div_fmas_f32 v131, v131, v143, v162
	v_div_fixup_f32 v141, v131, v141, 1.0
	v_div_scale_f32 v131, s[30:31], v140, v140, 1.0
	v_rcp_f32_e32 v143, v131
	s_nop 0
	v_fma_f32 v144, -v131, v143, 1.0
	v_fmac_f32_e32 v143, v144, v143
	v_div_scale_f32 v144, vcc, 1.0, v140, 1.0
	v_mul_f32_e32 v162, v144, v143
	v_fma_f32 v163, -v131, v162, v144
	v_fmac_f32_e32 v162, v163, v143
	v_fma_f32 v131, -v131, v162, v144
	v_div_fmas_f32 v131, v131, v143, v162
	v_div_fixup_f32 v140, v131, v140, 1.0
	v_mul_f32_e32 v131, 0xbfb8aa3b, v145
	v_exp_f32_e32 v143, v131
	v_pk_mul_f32 v[140:141], v[28:29], v[140:141]
	v_pk_add_f32 v[142:143], v[142:143], 1.0 op_sel_hi:[1,0]
	s_nop 0
	v_div_scale_f32 v131, s[30:31], v143, v143, 1.0
	v_rcp_f32_e32 v144, v131
	v_cvt_pk_bf16_f32 v137, v140, v141
	v_fma_f32 v145, -v131, v144, 1.0
	v_fmac_f32_e32 v144, v145, v144
	v_div_scale_f32 v145, vcc, 1.0, v143, 1.0
	v_mul_f32_e32 v162, v145, v144
	v_fma_f32 v163, -v131, v162, v145
	v_fmac_f32_e32 v162, v163, v144
	v_fma_f32 v131, -v131, v162, v145
	v_div_fmas_f32 v131, v131, v144, v162
	v_div_fixup_f32 v143, v131, v143, 1.0
	v_div_scale_f32 v131, s[30:31], v142, v142, 1.0
	v_rcp_f32_e32 v144, v131
	s_nop 0
	v_fma_f32 v145, -v131, v144, 1.0
	v_fmac_f32_e32 v144, v145, v144
	v_div_scale_f32 v145, vcc, 1.0, v142, 1.0
	v_mul_f32_e32 v162, v145, v144
	v_fma_f32 v163, -v131, v162, v145
	v_fmac_f32_e32 v162, v163, v144
	v_fma_f32 v131, -v131, v162, v145
	v_div_fmas_f32 v131, v131, v144, v162
	v_div_fixup_f32 v142, v131, v142, 1.0
	v_pk_mul_f32 v[142:143], v[20:21], v[142:143]
	s_nop 0
	v_cvt_pk_bf16_f32 v139, v142, v143
	global_store_dwordx4 v[134:135], v[136:139], off offset:256
	v_add_u32_e32 v134, 0xb0, v130
	v_ashrrev_i32_e32 v135, 31, v134
	v_lshlrev_b64 v[130:131], 12, v[134:135]
	v_lshl_add_u64 v[130:131], s[26:27], 0, v[130:131]
	v_mad_i64_i32 v[132:133], s[26:27], v134, s79, v[132:133]
	v_lshl_add_u64 v[132:133], v[132:133], 0, s[28:29]
	v_lshl_add_u64 v[134:135], v[132:133], 0, v[0:1]
	v_lshl_add_u64 v[132:133], v[134:135], 0, s[60:61]
	v_add_co_u32_e32 v134, vcc, s17, v134
	v_lshl_add_u64 v[130:131], v[130:131], 0, v[0:1]
	s_nop 0
	v_addc_co_u32_e32 v135, vcc, 0, v135, vcc
	s_waitcnt vmcnt(13)
; __device__ __forceinline__ unsigned pk2(float lo, float hi) { return pg8::cvt_pk_bf16(lo, hi); }
; __device__ __forceinline__ float sigmoidf_(float x) { return 1.f / (1.f + __expf(-x)); }
;     __device__ __forceinline__ void operator()(const f32x4 (&acc)[2][2][4][2], const pg8::Unit& u, int wr, int wc, int fr, int fq) const {
;     ...
;                     const u32x4 gw = *(const u32x4*)(P + (size_t)row * NINP + GATEOFF + (gi - 1) * 2048 + col); float gt[8]; unpack8(gw, gt);
;                     const f32x4 v0 = acc[ai][bj][m][0], v1 = acc[ai][bj][m][1];
;                     float o[8];
; #pragma unroll
;                     for (int j = 0; j < 4; ++j) { o[j] = sigmoidf_(gt[j]) * v0[j]; o[4 + j] = sigmoidf_(gt[4 + j]) * v1[j]; }
;                     u32x4 w; w.x = pk2(o[0], o[1]); w.y = pk2(o[2], o[3]); w.z = pk2(o[4], o[5]); w.w = pk2(o[6], o[7]);
;                     *(u32x4*)(br + (size_t)row * D + col) = w; } }
	s_nop 1
	v_mov_b32_e32 v134, v168
	v_mov_b32_e32 v135, v169
	v_mov_b32_e32 v136, v170
	v_mov_b32_e32 v137, v171
	v_lshlrev_b32_e32 v140, 16, v135
	v_and_b32_e32 v141, 0xffff0000, v135
	v_lshlrev_b32_e32 v135, 16, v136
	v_lshlrev_b32_e32 v138, 16, v134
	v_and_b32_e32 v139, 0xffff0000, v134
	v_mul_f32_e32 v135, 0xbfb8aa3b, v135
	v_and_b32_e32 v142, 0xffff0000, v136
	v_mul_f32_e32 v134, 0xbfb8aa3b, v138
	v_exp_f32_e32 v136, v135
	v_mul_f32_e32 v135, 0xbfb8aa3b, v139
	v_exp_f32_e32 v134, v134
	v_exp_f32_e32 v135, v135
	v_lshlrev_b32_e32 v143, 16, v137
	v_and_b32_e32 v144, 0xffff0000, v137
	v_pk_add_f32 v[134:135], v[134:135], 1.0 op_sel_hi:[1,0]
	s_nop 0
	v_div_scale_f32 v137, s[26:27], v135, v135, 1.0
	v_rcp_f32_e32 v138, v137
	s_nop 0
	v_fma_f32 v139, -v137, v138, 1.0
	v_fmac_f32_e32 v138, v139, v138
	v_div_scale_f32 v139, vcc, 1.0, v135, 1.0
	v_mul_f32_e32 v145, v139, v138
	v_fma_f32 v162, -v137, v145, v139
	v_fmac_f32_e32 v145, v162, v138
	v_fma_f32 v137, -v137, v145, v139
	v_div_fmas_f32 v137, v137, v138, v145
	v_div_fixup_f32 v135, v137, v135, 1.0
	v_div_scale_f32 v137, s[26:27], v134, v134, 1.0
	v_rcp_f32_e32 v138, v137
	s_nop 0
	v_fma_f32 v139, -v137, v138, 1.0
	v_fmac_f32_e32 v138, v139, v138
	v_div_scale_f32 v139, vcc, 1.0, v134, 1.0
	v_mul_f32_e32 v145, v139, v138
	v_fma_f32 v162, -v137, v145, v139
	v_fmac_f32_e32 v145, v162, v138
	v_fma_f32 v137, -v137, v145, v139
	v_div_fmas_f32 v137, v137, v138, v145
	v_div_fixup_f32 v134, v137, v134, 1.0
	v_mul_f32_e32 v137, 0xbfb8aa3b, v142
	v_exp_f32_e32 v137, v137
	v_pk_mul_f32 v[134:135], v[14:15], v[134:135]
	v_pk_add_f32 v[136:137], v[136:137], 1.0 op_sel_hi:[1,0]
	s_nop 0
	v_div_scale_f32 v138, s[26:27], v137, v137, 1.0
	v_rcp_f32_e32 v139, v138
	v_cvt_pk_bf16_f32 v134, v134, v135
	v_fma_f32 v142, -v138, v139, 1.0
	v_fmac_f32_e32 v139, v142, v139
	v_div_scale_f32 v142, vcc, 1.0, v137, 1.0
	v_mul_f32_e32 v145, v142, v139
	v_fma_f32 v162, -v138, v145, v142
	v_fmac_f32_e32 v145, v162, v139
	v_fma_f32 v138, -v138, v145, v142
	v_div_fmas_f32 v138, v138, v139, v145
	v_div_fixup_f32 v137, v138, v137, 1.0
	v_div_scale_f32 v138, s[26:27], v136, v136, 1.0
	v_rcp_f32_e32 v139, v138
	s_nop 0
	v_fma_f32 v142, -v138, v139, 1.0
	v_fmac_f32_e32 v139, v142, v139
	v_div_scale_f32 v142, vcc, 1.0, v136, 1.0
	v_mul_f32_e32 v145, v142, v139
	v_fma_f32 v162, -v138, v145, v142
	v_fmac_f32_e32 v145, v162, v139
	v_fma_f32 v138, -v138, v145, v142
	v_div_fmas_f32 v138, v138, v139, v145
	v_mul_f32_e32 v139, 0xbfb8aa3b, v143
	v_div_fixup_f32 v136, v138, v136, 1.0
	v_mul_f32_e32 v138, 0xbfb8aa3b, v140
	v_exp_f32_e32 v140, v139
	v_mul_f32_e32 v139, 0xbfb8aa3b, v141
	v_exp_f32_e32 v138, v138
	v_exp_f32_e32 v139, v139
	v_pk_mul_f32 v[136:137], v[6:7], v[136:137]
	v_pk_add_f32 v[138:139], v[138:139], 1.0 op_sel_hi:[1,0]
	s_nop 0
	v_div_scale_f32 v141, s[26:27], v139, v139, 1.0
	v_rcp_f32_e32 v142, v141
	v_cvt_pk_bf16_f32 v136, v136, v137
	v_fma_f32 v143, -v141, v142, 1.0
	v_fmac_f32_e32 v142, v143, v142
	v_div_scale_f32 v143, vcc, 1.0, v139, 1.0
	v_mul_f32_e32 v145, v143, v142
	v_fma_f32 v162, -v141, v145, v143
	v_fmac_f32_e32 v145, v162, v142
	v_fma_f32 v141, -v141, v145, v143
	v_div_fmas_f32 v141, v141, v142, v145
	v_div_fixup_f32 v139, v141, v139, 1.0
	v_div_scale_f32 v141, s[26:27], v138, v138, 1.0
	v_rcp_f32_e32 v142, v141
	s_nop 0
	v_fma_f32 v143, -v141, v142, 1.0
	v_fmac_f32_e32 v142, v143, v142
	v_div_scale_f32 v143, vcc, 1.0, v138, 1.0
	v_mul_f32_e32 v145, v143, v142
	v_fma_f32 v162, -v141, v145, v143
	v_fmac_f32_e32 v145, v162, v142
	v_fma_f32 v141, -v141, v145, v143
	v_div_fmas_f32 v141, v141, v142, v145
	v_div_fixup_f32 v138, v141, v138, 1.0
	v_mul_f32_e32 v141, 0xbfb8aa3b, v144
	v_exp_f32_e32 v141, v141
	v_pk_mul_f32 v[138:139], v[16:17], v[138:139]
	v_pk_add_f32 v[140:141], v[140:141], 1.0 op_sel_hi:[1,0]
	s_nop 0
	v_div_scale_f32 v142, s[26:27], v141, v141, 1.0
	v_rcp_f32_e32 v143, v142
	v_cvt_pk_bf16_f32 v135, v138, v139
	v_fma_f32 v144, -v142, v143, 1.0
	v_fmac_f32_e32 v143, v144, v143
	v_div_scale_f32 v144, vcc, 1.0, v141, 1.0
	v_mul_f32_e32 v145, v144, v143
	v_fma_f32 v162, -v142, v145, v144
	v_fmac_f32_e32 v145, v162, v143
	v_fma_f32 v142, -v142, v145, v144
	v_div_fmas_f32 v142, v142, v143, v145
	v_div_fixup_f32 v141, v142, v141, 1.0
	v_div_scale_f32 v142, s[26:27], v140, v140, 1.0
	v_rcp_f32_e32 v143, v142
	s_nop 0
	v_fma_f32 v144, -v142, v143, 1.0
	v_fmac_f32_e32 v143, v144, v143
	v_div_scale_f32 v144, vcc, 1.0, v140, 1.0
	v_mul_f32_e32 v145, v144, v143
	v_fma_f32 v162, -v142, v145, v144
	v_fmac_f32_e32 v145, v162, v143
	v_fma_f32 v142, -v142, v145, v144
	v_div_fmas_f32 v142, v142, v143, v145
	v_div_fixup_f32 v140, v142, v140, 1.0
	v_pk_mul_f32 v[140:141], v[8:9], v[140:141]
	s_nop 0
	v_cvt_pk_bf16_f32 v137, v140, v141
	global_store_dwordx4 v[130:131], v[134:137], off
	s_waitcnt vmcnt(13)
; __device__ __forceinline__ unsigned pk2(float lo, float hi) { return pg8::cvt_pk_bf16(lo, hi); }
; __device__ __forceinline__ float sigmoidf_(float x) { return 1.f / (1.f + __expf(-x)); }
;     __device__ __forceinline__ void operator()(const f32x4 (&acc)[2][2][4][2], const pg8::Unit& u, int wr, int wc, int fr, int fq) const {
;     ...
;                     const u32x4 gw = *(const u32x4*)(P + (size_t)row * NINP + GATEOFF + (gi - 1) * 2048 + col); float gt[8]; unpack8(gw, gt);
;                     const f32x4 v0 = acc[ai][bj][m][0], v1 = acc[ai][bj][m][1];
;                     float o[8];
; #pragma unroll
;                     for (int j = 0; j < 4; ++j) { o[j] = sigmoidf_(gt[j]) * v0[j]; o[4 + j] = sigmoidf_(gt[4 + j]) * v1[j]; }
;                     u32x4 w; w.x = pk2(o[0], o[1]); w.y = pk2(o[2], o[3]); w.z = pk2(o[4], o[5]); w.w = pk2(o[6], o[7]);
;                     *(u32x4*)(br + (size_t)row * D + col) = w; } }
	s_nop 1
	v_mov_b32_e32 v132, v172
	v_mov_b32_e32 v133, v173
	v_mov_b32_e32 v134, v174
	v_mov_b32_e32 v135, v175
	v_lshlrev_b32_e32 v0, 16, v132
	v_lshlrev_b32_e32 v137, 16, v133
	v_and_b32_e32 v139, 0xffff0000, v133
	v_lshlrev_b32_e32 v133, 16, v134
	v_mul_f32_e32 v0, 0xbfb8aa3b, v0
	v_and_b32_e32 v136, 0xffff0000, v132
	v_exp_f32_e32 v132, v0
	v_mul_f32_e32 v0, 0xbfb8aa3b, v133
	v_and_b32_e32 v138, 0xffff0000, v134
	v_exp_f32_e32 v134, v0
	v_mul_f32_e32 v0, 0xbfb8aa3b, v136
	v_exp_f32_e32 v133, v0
	v_lshlrev_b32_e32 v140, 16, v135
	v_and_b32_e32 v141, 0xffff0000, v135
	v_pk_add_f32 v[132:133], v[132:133], 1.0 op_sel_hi:[1,0]
	s_nop 0
	v_div_scale_f32 v0, s[26:27], v133, v133, 1.0
	v_rcp_f32_e32 v135, v0
	s_nop 0
	v_fma_f32 v136, -v0, v135, 1.0
	v_fmac_f32_e32 v135, v136, v135
	v_div_scale_f32 v136, vcc, 1.0, v133, 1.0
	v_mul_f32_e32 v142, v136, v135
	v_fma_f32 v143, -v0, v142, v136
	v_fmac_f32_e32 v142, v143, v135
	v_fma_f32 v0, -v0, v142, v136
	v_div_fmas_f32 v0, v0, v135, v142
	v_div_fixup_f32 v133, v0, v133, 1.0
	v_div_scale_f32 v0, s[26:27], v132, v132, 1.0
	v_rcp_f32_e32 v135, v0
	s_nop 0
	v_fma_f32 v136, -v0, v135, 1.0
	v_fmac_f32_e32 v135, v136, v135
	v_div_scale_f32 v136, vcc, 1.0, v132, 1.0
	v_mul_f32_e32 v142, v136, v135
	v_fma_f32 v143, -v0, v142, v136
	v_fmac_f32_e32 v142, v143, v135
	v_fma_f32 v0, -v0, v142, v136
	v_div_fmas_f32 v0, v0, v135, v142
	v_div_fixup_f32 v132, v0, v132, 1.0
	v_mul_f32_e32 v0, 0xbfb8aa3b, v138
	v_exp_f32_e32 v135, v0
	v_pk_mul_f32 v[132:133], v[10:11], v[132:133]
	v_pk_add_f32 v[134:135], v[134:135], 1.0 op_sel_hi:[1,0]
	s_nop 0
	v_div_scale_f32 v0, s[26:27], v135, v135, 1.0
	v_rcp_f32_e32 v136, v0
	v_cvt_pk_bf16_f32 v132, v132, v133
	v_fma_f32 v138, -v0, v136, 1.0
	v_fmac_f32_e32 v136, v138, v136
	v_div_scale_f32 v138, vcc, 1.0, v135, 1.0
	v_mul_f32_e32 v142, v138, v136
	v_fma_f32 v143, -v0, v142, v138
	v_fmac_f32_e32 v142, v143, v136
	v_fma_f32 v0, -v0, v142, v138
	v_div_fmas_f32 v0, v0, v136, v142
	v_div_fixup_f32 v135, v0, v135, 1.0
	v_div_scale_f32 v0, s[26:27], v134, v134, 1.0
	v_rcp_f32_e32 v136, v0
	s_nop 0
	v_fma_f32 v138, -v0, v136, 1.0
	v_fmac_f32_e32 v136, v138, v136
	v_div_scale_f32 v138, vcc, 1.0, v134, 1.0
	v_mul_f32_e32 v142, v138, v136
	v_fma_f32 v143, -v0, v142, v138
	v_fmac_f32_e32 v142, v143, v136
	v_fma_f32 v0, -v0, v142, v138
	v_div_fmas_f32 v0, v0, v136, v142
	v_div_fixup_f32 v134, v0, v134, 1.0
	v_mul_f32_e32 v0, 0xbfb8aa3b, v137
	v_exp_f32_e32 v136, v0
	v_mul_f32_e32 v0, 0xbfb8aa3b, v140
	v_exp_f32_e32 v138, v0
	v_mul_f32_e32 v0, 0xbfb8aa3b, v139
	v_exp_f32_e32 v137, v0
	v_pk_mul_f32 v[134:135], v[2:3], v[134:135]
	v_pk_add_f32 v[136:137], v[136:137], 1.0 op_sel_hi:[1,0]
	s_nop 0
	v_div_scale_f32 v0, s[26:27], v137, v137, 1.0
	v_rcp_f32_e32 v139, v0
	v_cvt_pk_bf16_f32 v134, v134, v135
	v_fma_f32 v140, -v0, v139, 1.0
	v_fmac_f32_e32 v139, v140, v139
	v_div_scale_f32 v140, vcc, 1.0, v137, 1.0
	v_mul_f32_e32 v142, v140, v139
	v_fma_f32 v143, -v0, v142, v140
	v_fmac_f32_e32 v142, v143, v139
	v_fma_f32 v0, -v0, v142, v140
	v_div_fmas_f32 v0, v0, v139, v142
	v_div_fixup_f32 v137, v0, v137, 1.0
	v_div_scale_f32 v0, s[26:27], v136, v136, 1.0
	v_rcp_f32_e32 v139, v0
	s_nop 0
	v_fma_f32 v140, -v0, v139, 1.0
	v_fmac_f32_e32 v139, v140, v139
	v_div_scale_f32 v140, vcc, 1.0, v136, 1.0
	v_mul_f32_e32 v142, v140, v139
	v_fma_f32 v143, -v0, v142, v140
	v_fmac_f32_e32 v142, v143, v139
	v_fma_f32 v0, -v0, v142, v140
	v_div_fmas_f32 v0, v0, v139, v142
	v_div_fixup_f32 v136, v0, v136, 1.0
	v_mul_f32_e32 v0, 0xbfb8aa3b, v141
	v_exp_f32_e32 v139, v0
	v_pk_mul_f32 v[136:137], v[12:13], v[136:137]
	v_pk_add_f32 v[138:139], v[138:139], 1.0 op_sel_hi:[1,0]
	s_nop 0
	v_div_scale_f32 v0, s[26:27], v139, v139, 1.0
	v_rcp_f32_e32 v140, v0
	v_cvt_pk_bf16_f32 v133, v136, v137
	v_fma_f32 v141, -v0, v140, 1.0
	v_fmac_f32_e32 v140, v141, v140
	v_div_scale_f32 v141, vcc, 1.0, v139, 1.0
	v_mul_f32_e32 v142, v141, v140
	v_fma_f32 v143, -v0, v142, v141
	v_fmac_f32_e32 v142, v143, v140
	v_fma_f32 v0, -v0, v142, v141
	v_div_fmas_f32 v0, v0, v140, v142
	v_div_fixup_f32 v139, v0, v139, 1.0
	v_div_scale_f32 v0, s[26:27], v138, v138, 1.0
	v_rcp_f32_e32 v140, v0
	s_mov_b64 s[26:27], 0
	v_fma_f32 v141, -v0, v140, 1.0
	v_fmac_f32_e32 v140, v141, v140
	v_div_scale_f32 v141, vcc, 1.0, v138, 1.0
	v_mul_f32_e32 v142, v141, v140
	v_fma_f32 v143, -v0, v142, v141
	v_fmac_f32_e32 v142, v143, v140
	v_fma_f32 v0, -v0, v142, v141
	v_div_fmas_f32 v0, v0, v140, v142
	v_div_fixup_f32 v138, v0, v138, 1.0
	v_pk_mul_f32 v[138:139], v[4:5], v[138:139]
	s_nop 0
	v_cvt_pk_bf16_f32 v135, v138, v139
	global_store_dwordx4 v[130:131], v[132:135], off offset:256
